# GEMM K-loop heads: next-tile pointer selects (7 SALU) moved behind the SP1 LDS reads/DMA, so the 16 ds_reads issue first; on top of no-setprio version
# speedup vs baseline: 1.0058x; 1.0058x over previous
; #define PG8_STAGE(bufoff, gbase, voff) do { _Pragma("unroll") for (int _i = 0; _i < 2; ++_i) \
;         __builtin_amdgcn_global_load_lds((const unsigned*)((const char*)(gbase) + (voff)[_i]), (LAS unsigned*)(lds + (bufoff) + ldsw + _i * 8192), 16, 0, 0); } while (0)
; #define PG8_LDA(dst, b, h) do { _Pragma("unroll") for (int m = 0; m < 4; ++m) _Pragma("unroll") for (int k = 0; k < 2; ++k) dst[m][k] = *(const LAS bf16x8*)(lds + PG8_SA(b, h) + aoff + m * 2048 + k * 1024); } while (0)
; #define PG8_LDB(dst, b, h) do { _Pragma("unroll") for (int n = 0; n < 2; ++n) _Pragma("unroll") for (int k = 0; k < 2; ++k) dst[n][k] = *(const LAS bf16x8*)(lds + PG8_SB(b, h) + boff + n * 2048 + k * 1024); } while (0)
; #define PG8_MMA(ai, bj, At, Bt) do { __builtin_amdgcn_s_setprio(1); _Pragma("unroll") for (int m = 0; m < 4; ++m) _Pragma("unroll") for (int n = 0; n < 2; ++n) _Pragma("unroll") for (int k = 0; k < 2; ++k) \
;         acc[ai][bj][m][n] = __builtin_amdgcn_mfma_f32_16x16x32_bf16(Bt[n][k], At[m][k], acc[ai][bj][m][n], 0, 0, 0); __builtin_amdgcn_s_setprio(0); } while (0)
; #define PG8_WAIT_V(n) asm volatile("s_waitcnt vmcnt(" #n ")" ::: "memory")
; #define PG8_WAIT_L(n) asm volatile("s_waitcnt lgkmcnt(" #n ")" ::: "memory")
; #define PG8_BAR __builtin_amdgcn_s_barrier()
; #define PG8_SCHED __builtin_amdgcn_sched_barrier(0)
; template <class Epi, class Sched>
; DI void gemm_phase(LAS unsigned char* lds, const int wv, const int lda, const int ldb, const Sched& S, const Epi& E) {
;     ...
;             const bool last = (t == nt - 2);
;             const char* a1 = cA + (size_t)(t + 1) * kstep;
;             const char* a2 = last ? nA : cA + (size_t)(t + 2) * kstep; const char* b2 = last ? nB : cB + (size_t)(t + 2) * kstep;
;             const char* a3 = a2 + kstep; const char* b3 = b2 + kstep;
;             PG8_LDB(B0, 0, 0); PG8_LDB(B1, 0, 1); PG8_SCHED; PG8_LDA(At, 0, 0); PG8_STAGE(PG8_SA(1, 1), a1 + hstepA, voffA);
;             PG8_WAIT_V(8); PG8_WAIT_L(0); PG8_BAR; PG8_MMA(0, 0, At, B0); PG8_MMA(0, 1, At, B1); PG8_BAR; PG8_SCHED;
;             PG8_LDA(At, 0, 1); PG8_STAGE(PG8_SB(0, 0), b2, voffB); PG8_STAGE(PG8_SB(0, 1), b2 + hstepB, voffB); PG8_STAGE(PG8_SA(0, 0), a2, voffA);
;             PG8_WAIT_V(8); PG8_WAIT_L(0); PG8_BAR; PG8_MMA(1, 0, At, B0); PG8_MMA(1, 1, At, B1); PG8_BAR; PG8_SCHED;
.LBB0_378:
	s_add_i32 s61, 0, 0x10000
	s_add_i32 s33, 0, 0x14000
	v_add_u32_e32 v154, s61, v170
	v_add_u32_e32 v173, s33, v170
	ds_read_b128 v[104:107], v154
	ds_read_b128 v[108:111], v154 offset:1024
	ds_read_b128 v[150:153], v154 offset:2048
	ds_read_b128 v[154:157], v154 offset:3072
	ds_read_b128 v[158:161], v173
	ds_read_b128 v[162:165], v173 offset:1024
	ds_read_b128 v[166:169], v173 offset:2048
	ds_read_b128 v[174:177], v173 offset:3072
	v_lshl_add_u64 v[182:183], s[34:35], 0, v[146:147]
	s_add_i32 m0, s31, 0xc000
	ds_read_b128 v[178:181], v172
	ds_read_b128 v[200:203], v172 offset:1024
	ds_read_b128 v[204:207], v172 offset:2048
	ds_read_b128 v[208:211], v172 offset:3072
	ds_read_b128 v[212:215], v172 offset:4096
	ds_read_b128 v[216:219], v172 offset:5120
	ds_read_b128 v[220:223], v172 offset:6144
	ds_read_b128 v[234:237], v172 offset:7168
	global_load_lds_dwordx4 v[182:183], off
	v_lshl_add_u64 v[182:183], s[34:35], 0, v[148:149]
	s_add_i32 m0, s31, 0xe000
	s_nop 0
	global_load_lds_dwordx4 v[182:183], off
	s_add_u32 s98, s34, 0xfff80080
	s_addc_u32 s36, s35, -1
	s_cmp_eq_u32 s23, 28
	s_cselect_b32 s39, s0, s36
	s_cselect_b32 s38, s1, s98
	s_cselect_b32 s37, s5, s19
	s_cselect_b32 s36, s16, s17
	s_waitcnt vmcnt(8)
	s_waitcnt lgkmcnt(0)
	s_barrier
	s_waitcnt lgkmcnt(0)
	v_mfma_f32_16x16x32_bf16 v[132:135], v[104:107], v[178:181], v[132:135]
	v_mfma_f32_16x16x32_bf16 v[128:131], v[150:153], v[178:181], v[128:131]
	v_mfma_f32_16x16x32_bf16 v[124:127], v[104:107], v[204:207], v[124:127]
	v_mfma_f32_16x16x32_bf16 v[120:123], v[150:153], v[204:207], v[120:123]
	v_mfma_f32_16x16x32_bf16 v[116:119], v[104:107], v[212:215], v[116:119]
	v_mfma_f32_16x16x32_bf16 v[112:115], v[150:153], v[212:215], v[112:115]
	v_mfma_f32_16x16x32_bf16 v[100:103], v[104:107], v[220:223], v[100:103]
	v_mfma_f32_16x16x32_bf16 v[96:99], v[150:153], v[220:223], v[96:99]
	v_mfma_f32_16x16x32_bf16 v[132:135], v[108:111], v[200:203], v[132:135]
	v_mfma_f32_16x16x32_bf16 v[128:131], v[154:157], v[200:203], v[128:131]
	v_mfma_f32_16x16x32_bf16 v[124:127], v[108:111], v[208:211], v[124:127]
	v_mfma_f32_16x16x32_bf16 v[120:123], v[154:157], v[208:211], v[120:123]
	v_mfma_f32_16x16x32_bf16 v[116:119], v[108:111], v[216:219], v[116:119]
	v_mfma_f32_16x16x32_bf16 v[112:115], v[154:157], v[216:219], v[112:115]
	v_mfma_f32_16x16x32_bf16 v[100:103], v[108:111], v[234:237], v[100:103]
	v_mfma_f32_16x16x32_bf16 v[96:99], v[154:157], v[234:237], v[96:99]
	v_mfma_f32_16x16x32_bf16 v[60:63], v[158:161], v[178:181], v[60:63]
	v_mfma_f32_16x16x32_bf16 v[56:59], v[166:169], v[178:181], v[56:59]
	v_mfma_f32_16x16x32_bf16 v[52:55], v[158:161], v[204:207], v[52:55]
	v_mfma_f32_16x16x32_bf16 v[48:51], v[166:169], v[204:207], v[48:51]
	v_mfma_f32_16x16x32_bf16 v[44:47], v[158:161], v[212:215], v[44:47]
	v_mfma_f32_16x16x32_bf16 v[40:43], v[166:169], v[212:215], v[40:43]
	v_mfma_f32_16x16x32_bf16 v[36:39], v[158:161], v[220:223], v[36:39]
	v_mfma_f32_16x16x32_bf16 v[32:35], v[166:169], v[220:223], v[32:35]
	v_mfma_f32_16x16x32_bf16 v[60:63], v[162:165], v[200:203], v[60:63]
	v_mfma_f32_16x16x32_bf16 v[56:59], v[174:177], v[200:203], v[56:59]
	v_mfma_f32_16x16x32_bf16 v[52:55], v[162:165], v[208:211], v[52:55]
	v_mfma_f32_16x16x32_bf16 v[48:51], v[174:177], v[208:211], v[48:51]
	v_mfma_f32_16x16x32_bf16 v[44:47], v[162:165], v[216:219], v[44:47]
	v_mfma_f32_16x16x32_bf16 v[40:43], v[174:177], v[216:219], v[40:43]
	v_mfma_f32_16x16x32_bf16 v[36:39], v[162:165], v[234:237], v[36:39]
	v_mfma_f32_16x16x32_bf16 v[32:35], v[174:177], v[234:237], v[32:35]
	s_barrier
	s_add_i32 s61, s61, s47
	v_lshl_add_u64 v[182:183], s[36:37], 0, v[138:139]
	s_mov_b32 m0, s61
	ds_read_b128 v[178:181], v172 offset:16384
	ds_read_b128 v[200:203], v172 offset:17408
	ds_read_b128 v[204:207], v172 offset:18432
	ds_read_b128 v[208:211], v172 offset:19456
	ds_read_b128 v[212:215], v172 offset:20480
	ds_read_b128 v[216:219], v172 offset:21504
	ds_read_b128 v[220:223], v172 offset:22528
	ds_read_b128 v[234:237], v172 offset:23552
	global_load_lds_dwordx4 v[182:183], off
	s_add_i32 m0, s61, 0x2000
	s_add_u32 s62, s36, 0x80000
	v_lshl_add_u64 v[188:189], s[36:37], 0, v[142:143]
	s_addc_u32 s63, s37, 0
	s_add_i32 s33, s33, s47
	global_load_lds_dwordx4 v[188:189], off
	v_lshl_add_u64 v[190:191], s[62:63], 0, v[138:139]
	s_mov_b32 m0, s33
	v_lshl_add_u64 v[196:197], s[38:39], 0, v[140:141]
	global_load_lds_dwordx4 v[190:191], off
	v_lshl_add_u64 v[190:191], s[62:63], 0, v[142:143]
	s_add_i32 m0, s33, 0x2000
	s_nop 0
	global_load_lds_dwordx4 v[190:191], off
	v_lshl_add_u64 v[190:191], s[38:39], 0, v[136:137]
	s_mov_b32 m0, s31
	s_nop 0
	global_load_lds_dwordx4 v[190:191], off
	s_mov_b32 m0, s48
	s_nop 0
	global_load_lds_dwordx4 v[196:197], off
	s_waitcnt vmcnt(8)
	s_waitcnt lgkmcnt(0)
	s_barrier
; #define PG8_STAGE(bufoff, gbase, voff) do { _Pragma("unroll") for (int _i = 0; _i < 2; ++_i) \
;         __builtin_amdgcn_global_load_lds((const unsigned*)((const char*)(gbase) + (voff)[_i]), (LAS unsigned*)(lds + (bufoff) + ldsw + _i * 8192), 16, 0, 0); } while (0)
; #define PG8_LDA(dst, b, h) do { _Pragma("unroll") for (int m = 0; m < 4; ++m) _Pragma("unroll") for (int k = 0; k < 2; ++k) dst[m][k] = *(const LAS bf16x8*)(lds + PG8_SA(b, h) + aoff + m * 2048 + k * 1024); } while (0)
; #define PG8_LDB(dst, b, h) do { _Pragma("unroll") for (int n = 0; n < 2; ++n) _Pragma("unroll") for (int k = 0; k < 2; ++k) dst[n][k] = *(const LAS bf16x8*)(lds + PG8_SB(b, h) + boff + n * 2048 + k * 1024); } while (0)
; #define PG8_MMA(ai, bj, At, Bt) do { __builtin_amdgcn_s_setprio(1); _Pragma("unroll") for (int m = 0; m < 4; ++m) _Pragma("unroll") for (int n = 0; n < 2; ++n) _Pragma("unroll") for (int k = 0; k < 2; ++k) \
;         acc[ai][bj][m][n] = __builtin_amdgcn_mfma_f32_16x16x32_bf16(Bt[n][k], At[m][k], acc[ai][bj][m][n], 0, 0, 0); __builtin_amdgcn_s_setprio(0); } while (0)
; #define PG8_WAIT_V(n) asm volatile("s_waitcnt vmcnt(" #n ")" ::: "memory")
; #define PG8_WAIT_L(n) asm volatile("s_waitcnt lgkmcnt(" #n ")" ::: "memory")
; #define PG8_BAR __builtin_amdgcn_s_barrier()
; #define PG8_SCHED __builtin_amdgcn_sched_barrier(0)
; template <class Epi, class Sched>
; DI void gemm_phase(LAS unsigned char* lds, const int wv, const int lda, const int ldb, const Sched& S, const Epi& E) {
;     ...
;             PG8_WAIT_V(8); PG8_WAIT_L(0); PG8_BAR; PG8_MMA(1, 0, At, B0); PG8_MMA(1, 1, At, B1); PG8_BAR; PG8_SCHED;
;             PG8_LDB(B0, 1, 0); PG8_LDB(B1, 1, 1); PG8_SCHED; PG8_LDA(At, 1, 0); PG8_STAGE(PG8_SA(0, 1), a2 + hstepA, voffA);
;             PG8_WAIT_V(8); PG8_WAIT_L(0); PG8_BAR; PG8_MMA(0, 0, At, B0); PG8_MMA(0, 1, At, B1); PG8_BAR; PG8_SCHED;
	s_waitcnt lgkmcnt(0)
	v_mfma_f32_16x16x32_bf16 v[92:95], v[104:107], v[178:181], v[92:95]
	v_mfma_f32_16x16x32_bf16 v[88:91], v[150:153], v[178:181], v[88:91]
	v_mfma_f32_16x16x32_bf16 v[84:87], v[104:107], v[204:207], v[84:87]
	v_mfma_f32_16x16x32_bf16 v[80:83], v[150:153], v[204:207], v[80:83]
	v_mfma_f32_16x16x32_bf16 v[76:79], v[104:107], v[212:215], v[76:79]
	v_mfma_f32_16x16x32_bf16 v[72:75], v[150:153], v[212:215], v[72:75]
	v_mfma_f32_16x16x32_bf16 v[68:71], v[104:107], v[220:223], v[68:71]
	v_mfma_f32_16x16x32_bf16 v[64:67], v[150:153], v[220:223], v[64:67]
	v_mfma_f32_16x16x32_bf16 v[92:95], v[108:111], v[200:203], v[92:95]
	v_mfma_f32_16x16x32_bf16 v[88:91], v[154:157], v[200:203], v[88:91]
	v_mfma_f32_16x16x32_bf16 v[84:87], v[108:111], v[208:211], v[84:87]
	v_mfma_f32_16x16x32_bf16 v[80:83], v[154:157], v[208:211], v[80:83]
	v_mfma_f32_16x16x32_bf16 v[76:79], v[108:111], v[216:219], v[76:79]
	v_mfma_f32_16x16x32_bf16 v[72:75], v[154:157], v[216:219], v[72:75]
	v_mfma_f32_16x16x32_bf16 v[68:71], v[108:111], v[234:237], v[68:71]
	v_mfma_f32_16x16x32_bf16 v[64:67], v[154:157], v[234:237], v[64:67]
	v_mfma_f32_16x16x32_bf16 v[28:31], v[158:161], v[178:181], v[28:31]
	v_mfma_f32_16x16x32_bf16 v[24:27], v[166:169], v[178:181], v[24:27]
	v_mfma_f32_16x16x32_bf16 v[20:23], v[158:161], v[204:207], v[20:23]
	v_mfma_f32_16x16x32_bf16 v[16:19], v[166:169], v[204:207], v[16:19]
	v_mfma_f32_16x16x32_bf16 v[12:15], v[158:161], v[212:215], v[12:15]
	v_mfma_f32_16x16x32_bf16 v[8:11], v[166:169], v[212:215], v[8:11]
	v_mfma_f32_16x16x32_bf16 v[4:7], v[158:161], v[220:223], v[4:7]
	v_mfma_f32_16x16x32_bf16 v[0:3], v[166:169], v[220:223], v[0:3]
	v_mfma_f32_16x16x32_bf16 v[28:31], v[162:165], v[200:203], v[28:31]
	v_mfma_f32_16x16x32_bf16 v[24:27], v[174:177], v[200:203], v[24:27]
	v_mfma_f32_16x16x32_bf16 v[20:23], v[162:165], v[208:211], v[20:23]
	v_mfma_f32_16x16x32_bf16 v[16:19], v[174:177], v[208:211], v[16:19]
	v_mfma_f32_16x16x32_bf16 v[12:15], v[162:165], v[216:219], v[12:15]
	v_mfma_f32_16x16x32_bf16 v[8:11], v[174:177], v[216:219], v[8:11]
	v_mfma_f32_16x16x32_bf16 v[4:7], v[162:165], v[234:237], v[4:7]
	v_mfma_f32_16x16x32_bf16 v[0:3], v[174:177], v[234:237], v[0:3]
	s_barrier
	s_add_i32 s33, 0, 0x18000
	s_add_i32 s61, 0, 0x1c000
	v_add_u32_e32 v154, s33, v170
	v_add_u32_e32 v173, s61, v170
	ds_read_b128 v[104:107], v154
	ds_read_b128 v[108:111], v154 offset:1024
	ds_read_b128 v[150:153], v154 offset:2048
	ds_read_b128 v[154:157], v154 offset:3072
	ds_read_b128 v[158:161], v173
	ds_read_b128 v[162:165], v173 offset:1024
	ds_read_b128 v[166:169], v173 offset:2048
	ds_read_b128 v[174:177], v173 offset:3072
	s_add_u32 s38, s38, 0x80000
	s_addc_u32 s39, s39, 0
	s_mov_b32 m0, s49
	v_lshl_add_u64 v[198:199], s[38:39], 0, v[136:137]
	ds_read_b128 v[178:181], v172 offset:32768
	ds_read_b128 v[200:203], v172 offset:33792
	ds_read_b128 v[204:207], v172 offset:34816
	ds_read_b128 v[208:211], v172 offset:35840
	ds_read_b128 v[212:215], v172 offset:36864
	ds_read_b128 v[216:219], v172 offset:37888
	ds_read_b128 v[220:223], v172 offset:38912
	ds_read_b128 v[234:237], v172 offset:39936
	global_load_lds_dwordx4 v[198:199], off
	v_lshl_add_u64 v[198:199], s[38:39], 0, v[140:141]
	s_mov_b32 m0, s50
	s_nop 0
	global_load_lds_dwordx4 v[198:199], off
	s_waitcnt vmcnt(8)
	s_waitcnt lgkmcnt(0)
	s_barrier
	s_waitcnt lgkmcnt(0)
	v_mfma_f32_16x16x32_bf16 v[132:135], v[104:107], v[178:181], v[132:135]
	v_mfma_f32_16x16x32_bf16 v[128:131], v[150:153], v[178:181], v[128:131]
	v_mfma_f32_16x16x32_bf16 v[124:127], v[104:107], v[204:207], v[124:127]
	v_mfma_f32_16x16x32_bf16 v[120:123], v[150:153], v[204:207], v[120:123]
	v_mfma_f32_16x16x32_bf16 v[116:119], v[104:107], v[212:215], v[116:119]
	v_mfma_f32_16x16x32_bf16 v[112:115], v[150:153], v[212:215], v[112:115]
	v_mfma_f32_16x16x32_bf16 v[100:103], v[104:107], v[220:223], v[100:103]
	v_mfma_f32_16x16x32_bf16 v[96:99], v[150:153], v[220:223], v[96:99]
	v_mfma_f32_16x16x32_bf16 v[132:135], v[108:111], v[200:203], v[132:135]
	v_mfma_f32_16x16x32_bf16 v[128:131], v[154:157], v[200:203], v[128:131]
	v_mfma_f32_16x16x32_bf16 v[124:127], v[108:111], v[208:211], v[124:127]
	v_mfma_f32_16x16x32_bf16 v[120:123], v[154:157], v[208:211], v[120:123]
	v_mfma_f32_16x16x32_bf16 v[116:119], v[108:111], v[216:219], v[116:119]
	v_mfma_f32_16x16x32_bf16 v[112:115], v[154:157], v[216:219], v[112:115]
	v_mfma_f32_16x16x32_bf16 v[100:103], v[108:111], v[234:237], v[100:103]
	v_mfma_f32_16x16x32_bf16 v[96:99], v[154:157], v[234:237], v[96:99]
	v_mfma_f32_16x16x32_bf16 v[60:63], v[158:161], v[178:181], v[60:63]
	v_mfma_f32_16x16x32_bf16 v[56:59], v[166:169], v[178:181], v[56:59]
	v_mfma_f32_16x16x32_bf16 v[52:55], v[158:161], v[204:207], v[52:55]
	v_mfma_f32_16x16x32_bf16 v[48:51], v[166:169], v[204:207], v[48:51]
	v_mfma_f32_16x16x32_bf16 v[44:47], v[158:161], v[212:215], v[44:47]
	v_mfma_f32_16x16x32_bf16 v[40:43], v[166:169], v[212:215], v[40:43]
	v_mfma_f32_16x16x32_bf16 v[36:39], v[158:161], v[220:223], v[36:39]
	v_mfma_f32_16x16x32_bf16 v[32:35], v[166:169], v[220:223], v[32:35]
	v_mfma_f32_16x16x32_bf16 v[60:63], v[162:165], v[200:203], v[60:63]
	v_mfma_f32_16x16x32_bf16 v[56:59], v[174:177], v[200:203], v[56:59]
	v_mfma_f32_16x16x32_bf16 v[52:55], v[162:165], v[208:211], v[52:55]
	v_mfma_f32_16x16x32_bf16 v[48:51], v[174:177], v[208:211], v[48:51]
	v_mfma_f32_16x16x32_bf16 v[44:47], v[162:165], v[216:219], v[44:47]
	v_mfma_f32_16x16x32_bf16 v[40:43], v[174:177], v[216:219], v[40:43]
	v_mfma_f32_16x16x32_bf16 v[36:39], v[162:165], v[234:237], v[36:39]
	v_mfma_f32_16x16x32_bf16 v[32:35], v[174:177], v[234:237], v[32:35]
	s_barrier
; #define PG8_STAGE(bufoff, gbase, voff) do { _Pragma("unroll") for (int _i = 0; _i < 2; ++_i) \
;         __builtin_amdgcn_global_load_lds((const unsigned*)((const char*)(gbase) + (voff)[_i]), (LAS unsigned*)(lds + (bufoff) + ldsw + _i * 8192), 16, 0, 0); } while (0)
; #define PG8_LDA(dst, b, h) do { _Pragma("unroll") for (int m = 0; m < 4; ++m) _Pragma("unroll") for (int k = 0; k < 2; ++k) dst[m][k] = *(const LAS bf16x8*)(lds + PG8_SA(b, h) + aoff + m * 2048 + k * 1024); } while (0)
; #define PG8_MMA(ai, bj, At, Bt) do { __builtin_amdgcn_s_setprio(1); _Pragma("unroll") for (int m = 0; m < 4; ++m) _Pragma("unroll") for (int n = 0; n < 2; ++n) _Pragma("unroll") for (int k = 0; k < 2; ++k) \
;         acc[ai][bj][m][n] = __builtin_amdgcn_mfma_f32_16x16x32_bf16(Bt[n][k], At[m][k], acc[ai][bj][m][n], 0, 0, 0); __builtin_amdgcn_s_setprio(0); } while (0)
; #define PG8_WAIT_V(n) asm volatile("s_waitcnt vmcnt(" #n ")" ::: "memory")
; #define PG8_WAIT_L(n) asm volatile("s_waitcnt lgkmcnt(" #n ")" ::: "memory")
; #define PG8_BAR __builtin_amdgcn_s_barrier()
; #define PG8_SCHED __builtin_amdgcn_sched_barrier(0)
; template <class Epi, class Sched>
; DI void gemm_phase(LAS unsigned char* lds, const int wv, const int lda, const int ldb, const Sched& S, const Epi& E) {
;     ...
;             PG8_LDA(At, 1, 1); PG8_STAGE(PG8_SB(1, 0), b3, voffB); PG8_STAGE(PG8_SB(1, 1), b3 + hstepB, voffB); PG8_STAGE(PG8_SA(1, 0), a3, voffA);
;             PG8_WAIT_V(8); PG8_WAIT_L(0); PG8_BAR; PG8_MMA(1, 0, At, B0); PG8_MMA(1, 1, At, B1); PG8_BAR; PG8_SCHED;
;         }
;         if (wr == 0) PG8_BAR;
	s_add_i32 s33, s33, s47
	v_lshl_add_u64 v[182:183], v[182:183], 0, s[28:29]
	s_mov_b32 m0, s33
	ds_read_b128 v[178:181], v172 offset:49152
	ds_read_b128 v[200:203], v172 offset:50176
	ds_read_b128 v[204:207], v172 offset:51200
	ds_read_b128 v[208:211], v172 offset:52224
	ds_read_b128 v[212:215], v172 offset:53248
	ds_read_b128 v[216:219], v172 offset:54272
	ds_read_b128 v[220:223], v172 offset:55296
	ds_read_b128 v[234:237], v172 offset:56320
	global_load_lds_dwordx4 v[182:183], off
	s_add_i32 m0, s33, 0x2000
	s_add_u32 s36, s36, 0x80080
	v_lshl_add_u64 v[182:183], v[188:189], 0, s[28:29]
	s_addc_u32 s37, s37, 0
	s_add_i32 s33, s61, s47
	global_load_lds_dwordx4 v[182:183], off
	v_lshl_add_u64 v[182:183], s[36:37], 0, v[138:139]
	s_mov_b32 m0, s33
	s_nop 0
	global_load_lds_dwordx4 v[182:183], off
	v_lshl_add_u64 v[182:183], s[36:37], 0, v[142:143]
	s_add_i32 m0, s33, 0x2000
	s_nop 0
	global_load_lds_dwordx4 v[182:183], off
	v_lshl_add_u64 v[182:183], v[190:191], 0, s[28:29]
	s_mov_b32 m0, s52
	s_nop 0
	global_load_lds_dwordx4 v[182:183], off
	v_lshl_add_u64 v[182:183], v[196:197], 0, s[28:29]
	s_mov_b32 m0, s53
	s_nop 0
	global_load_lds_dwordx4 v[182:183], off
	s_waitcnt vmcnt(8)
	s_waitcnt lgkmcnt(0)
	s_barrier
	s_waitcnt lgkmcnt(0)
	v_mfma_f32_16x16x32_bf16 v[92:95], v[104:107], v[178:181], v[92:95]
	v_mfma_f32_16x16x32_bf16 v[88:91], v[150:153], v[178:181], v[88:91]
	v_mfma_f32_16x16x32_bf16 v[84:87], v[104:107], v[204:207], v[84:87]
	v_mfma_f32_16x16x32_bf16 v[80:83], v[150:153], v[204:207], v[80:83]
	v_mfma_f32_16x16x32_bf16 v[76:79], v[104:107], v[212:215], v[76:79]
	v_mfma_f32_16x16x32_bf16 v[72:75], v[150:153], v[212:215], v[72:75]
	v_mfma_f32_16x16x32_bf16 v[68:71], v[104:107], v[220:223], v[68:71]
	v_mfma_f32_16x16x32_bf16 v[64:67], v[150:153], v[220:223], v[64:67]
	v_mfma_f32_16x16x32_bf16 v[92:95], v[108:111], v[200:203], v[92:95]
	v_mfma_f32_16x16x32_bf16 v[88:91], v[154:157], v[200:203], v[88:91]
	v_mfma_f32_16x16x32_bf16 v[84:87], v[108:111], v[208:211], v[84:87]
	v_mfma_f32_16x16x32_bf16 v[80:83], v[154:157], v[208:211], v[80:83]
	v_mfma_f32_16x16x32_bf16 v[76:79], v[108:111], v[216:219], v[76:79]
	v_mfma_f32_16x16x32_bf16 v[72:75], v[154:157], v[216:219], v[72:75]
	v_mfma_f32_16x16x32_bf16 v[68:71], v[108:111], v[234:237], v[68:71]
	v_mfma_f32_16x16x32_bf16 v[64:67], v[154:157], v[234:237], v[64:67]
	v_mfma_f32_16x16x32_bf16 v[28:31], v[158:161], v[178:181], v[28:31]
	v_mfma_f32_16x16x32_bf16 v[24:27], v[166:169], v[178:181], v[24:27]
	v_mfma_f32_16x16x32_bf16 v[20:23], v[158:161], v[204:207], v[20:23]
	v_mfma_f32_16x16x32_bf16 v[16:19], v[166:169], v[204:207], v[16:19]
	v_mfma_f32_16x16x32_bf16 v[12:15], v[158:161], v[212:215], v[12:15]
	v_mfma_f32_16x16x32_bf16 v[8:11], v[166:169], v[212:215], v[8:11]
	v_mfma_f32_16x16x32_bf16 v[4:7], v[158:161], v[220:223], v[4:7]
	v_mfma_f32_16x16x32_bf16 v[0:3], v[166:169], v[220:223], v[0:3]
	v_mfma_f32_16x16x32_bf16 v[28:31], v[162:165], v[200:203], v[28:31]
	v_mfma_f32_16x16x32_bf16 v[24:27], v[174:177], v[200:203], v[24:27]
	v_mfma_f32_16x16x32_bf16 v[20:23], v[162:165], v[208:211], v[20:23]
	v_mfma_f32_16x16x32_bf16 v[16:19], v[174:177], v[208:211], v[16:19]
	v_mfma_f32_16x16x32_bf16 v[12:15], v[162:165], v[216:219], v[12:15]
	v_mfma_f32_16x16x32_bf16 v[8:11], v[174:177], v[216:219], v[8:11]
	v_mfma_f32_16x16x32_bf16 v[4:7], v[162:165], v[234:237], v[4:7]
	v_mfma_f32_16x16x32_bf16 v[0:3], v[174:177], v[234:237], v[0:3]
	s_barrier
	s_add_i32 s23, s23, 2
	s_add_u32 s34, s34, 0x100
	s_addc_u32 s35, s35, 0
	s_add_u32 s17, s17, 0x100
	s_addc_u32 s19, s19, 0
	s_cmp_gt_u32 s23, 29
	s_cbranch_scc0 .LBB0_378
	s_and_b64 vcc, exec, s[14:15]
	s_cbranch_vccz .LBB0_381
	s_barrier

; #define PG8_STAGE(bufoff, gbase, voff) do { _Pragma("unroll") for (int _i = 0; _i < 2; ++_i) \
;         __builtin_amdgcn_global_load_lds((const unsigned*)((const char*)(gbase) + (voff)[_i]), (LAS unsigned*)(lds + (bufoff) + ldsw + _i * 8192), 16, 0, 0); } while (0)
; #define PG8_LDA(dst, b, h) do { _Pragma("unroll") for (int m = 0; m < 4; ++m) _Pragma("unroll") for (int k = 0; k < 2; ++k) dst[m][k] = *(const LAS bf16x8*)(lds + PG8_SA(b, h) + aoff + m * 2048 + k * 1024); } while (0)
; #define PG8_LDB(dst, b, h) do { _Pragma("unroll") for (int n = 0; n < 2; ++n) _Pragma("unroll") for (int k = 0; k < 2; ++k) dst[n][k] = *(const LAS bf16x8*)(lds + PG8_SB(b, h) + boff + n * 2048 + k * 1024); } while (0)
; #define PG8_MMA(ai, bj, At, Bt) do { __builtin_amdgcn_s_setprio(1); _Pragma("unroll") for (int m = 0; m < 4; ++m) _Pragma("unroll") for (int n = 0; n < 2; ++n) _Pragma("unroll") for (int k = 0; k < 2; ++k) \
;         acc[ai][bj][m][n] = __builtin_amdgcn_mfma_f32_16x16x32_bf16(Bt[n][k], At[m][k], acc[ai][bj][m][n], 0, 0, 0); __builtin_amdgcn_s_setprio(0); } while (0)
; #define PG8_WAIT_V(n) asm volatile("s_waitcnt vmcnt(" #n ")" ::: "memory")
; #define PG8_WAIT_L(n) asm volatile("s_waitcnt lgkmcnt(" #n ")" ::: "memory")
; #define PG8_BAR __builtin_amdgcn_s_barrier()
; #define PG8_SCHED __builtin_amdgcn_sched_barrier(0)
; template <class Epi, class Sched>
; DI void gemm_phase(LAS unsigned char* lds, const int wv, const int lda, const int ldb, const Sched& S, const Epi& E) {
;     ...
;             const bool last = (t == nt - 2);
;             const char* a1 = cA + (size_t)(t + 1) * kstep;
;             const char* a2 = last ? nA : cA + (size_t)(t + 2) * kstep; const char* b2 = last ? nB : cB + (size_t)(t + 2) * kstep;
;             const char* a3 = a2 + kstep; const char* b3 = b2 + kstep;
;             PG8_LDB(B0, 0, 0); PG8_LDB(B1, 0, 1); PG8_SCHED; PG8_LDA(At, 0, 0); PG8_STAGE(PG8_SA(1, 1), a1 + hstepA, voffA);
;             PG8_WAIT_V(8); PG8_WAIT_L(0); PG8_BAR; PG8_MMA(0, 0, At, B0); PG8_MMA(0, 1, At, B1); PG8_BAR; PG8_SCHED;
;             PG8_LDA(At, 0, 1); PG8_STAGE(PG8_SB(0, 0), b2, voffB); PG8_STAGE(PG8_SB(0, 1), b2 + hstepB, voffB); PG8_STAGE(PG8_SA(0, 0), a2, voffA);
;             PG8_WAIT_V(8); PG8_WAIT_L(0); PG8_BAR; PG8_MMA(1, 0, At, B0); PG8_MMA(1, 1, At, B1); PG8_BAR; PG8_SCHED;
.LBB0_1099:
	s_add_i32 s50, 0, 0x10000
	s_add_i32 s51, 0, 0x14000
	v_add_u32_e32 v108, s50, v204
	v_add_u32_e32 v156, s51, v204
	ds_read_b128 v[64:67], v108
	ds_read_b128 v[68:71], v108 offset:1024
	ds_read_b128 v[104:107], v108 offset:2048
	ds_read_b128 v[108:111], v108 offset:3072
	ds_read_b128 v[144:147], v156
	ds_read_b128 v[148:151], v156 offset:1024
	ds_read_b128 v[152:155], v156 offset:2048
	ds_read_b128 v[156:159], v156 offset:3072
	v_lshl_add_u64 v[182:183], s[22:23], 0, v[174:175]
	s_add_i32 m0, s38, 0xc000
	ds_read_b128 v[160:163], v206
	ds_read_b128 v[164:167], v206 offset:1024
	ds_read_b128 v[178:181], v206 offset:2048
	ds_read_b128 v[188:191], v206 offset:3072
	ds_read_b128 v[196:199], v206 offset:4096
	ds_read_b128 v[200:203], v206 offset:5120
	ds_read_b128 v[208:211], v206 offset:6144
	ds_read_b128 v[212:215], v206 offset:7168
	global_load_lds_dwordx4 v[182:183], off
	v_lshl_add_u64 v[182:183], s[22:23], 0, v[176:177]
	s_add_i32 m0, s38, 0xe000
	s_nop 0
	global_load_lds_dwordx4 v[182:183], off
	s_add_u32 s24, s22, 0x100
	s_addc_u32 s25, s23, 0
	s_cmp_eq_u32 s49, 8
	s_cselect_b32 s31, s7, s25
	s_cselect_b32 s30, s6, s24
	s_cselect_b32 s27, s19, s1
	s_cselect_b32 s26, s18, s0
	s_waitcnt vmcnt(8)
	s_waitcnt lgkmcnt(0)
	s_barrier
	s_waitcnt lgkmcnt(0)
	v_mfma_f32_16x16x32_bf16 v[140:143], v[64:67], v[160:163], v[140:143]
	v_mfma_f32_16x16x32_bf16 v[136:139], v[104:107], v[160:163], v[136:139]
	v_mfma_f32_16x16x32_bf16 v[132:135], v[64:67], v[178:181], v[132:135]
	v_mfma_f32_16x16x32_bf16 v[128:131], v[104:107], v[178:181], v[128:131]
	v_mfma_f32_16x16x32_bf16 v[124:127], v[64:67], v[196:199], v[124:127]
	v_mfma_f32_16x16x32_bf16 v[120:123], v[104:107], v[196:199], v[120:123]
	v_mfma_f32_16x16x32_bf16 v[116:119], v[64:67], v[208:211], v[116:119]
	v_mfma_f32_16x16x32_bf16 v[112:115], v[104:107], v[208:211], v[112:115]
	v_mfma_f32_16x16x32_bf16 v[140:143], v[68:71], v[164:167], v[140:143]
	v_mfma_f32_16x16x32_bf16 v[136:139], v[108:111], v[164:167], v[136:139]
	v_mfma_f32_16x16x32_bf16 v[132:135], v[68:71], v[188:191], v[132:135]
	v_mfma_f32_16x16x32_bf16 v[128:131], v[108:111], v[188:191], v[128:131]
	v_mfma_f32_16x16x32_bf16 v[124:127], v[68:71], v[200:203], v[124:127]
	v_mfma_f32_16x16x32_bf16 v[120:123], v[108:111], v[200:203], v[120:123]
	v_mfma_f32_16x16x32_bf16 v[116:119], v[68:71], v[212:215], v[116:119]
	v_mfma_f32_16x16x32_bf16 v[112:115], v[108:111], v[212:215], v[112:115]
	v_mfma_f32_16x16x32_bf16 v[100:103], v[144:147], v[160:163], v[100:103]
	v_mfma_f32_16x16x32_bf16 v[96:99], v[152:155], v[160:163], v[96:99]
	v_mfma_f32_16x16x32_bf16 v[92:95], v[144:147], v[178:181], v[92:95]
	v_mfma_f32_16x16x32_bf16 v[88:91], v[152:155], v[178:181], v[88:91]
	v_mfma_f32_16x16x32_bf16 v[84:87], v[144:147], v[196:199], v[84:87]
	v_mfma_f32_16x16x32_bf16 v[80:83], v[152:155], v[196:199], v[80:83]
	v_mfma_f32_16x16x32_bf16 v[76:79], v[144:147], v[208:211], v[76:79]
	v_mfma_f32_16x16x32_bf16 v[72:75], v[152:155], v[208:211], v[72:75]
	v_mfma_f32_16x16x32_bf16 v[100:103], v[148:151], v[164:167], v[100:103]
	v_mfma_f32_16x16x32_bf16 v[96:99], v[156:159], v[164:167], v[96:99]
	v_mfma_f32_16x16x32_bf16 v[92:95], v[148:151], v[188:191], v[92:95]
	v_mfma_f32_16x16x32_bf16 v[88:91], v[156:159], v[188:191], v[88:91]
	v_mfma_f32_16x16x32_bf16 v[84:87], v[148:151], v[200:203], v[84:87]
	v_mfma_f32_16x16x32_bf16 v[80:83], v[156:159], v[200:203], v[80:83]
	v_mfma_f32_16x16x32_bf16 v[76:79], v[148:151], v[212:215], v[76:79]
	v_mfma_f32_16x16x32_bf16 v[72:75], v[156:159], v[212:215], v[72:75]
	s_barrier
	s_add_i32 s22, s50, s36
	v_lshl_add_u64 v[182:183], s[26:27], 0, v[184:185]
	s_mov_b32 m0, s22
	ds_read_b128 v[160:163], v206 offset:16384
	ds_read_b128 v[164:167], v206 offset:17408
	ds_read_b128 v[178:181], v206 offset:18432
	ds_read_b128 v[188:191], v206 offset:19456
	ds_read_b128 v[196:199], v206 offset:20480
	ds_read_b128 v[200:203], v206 offset:21504
	ds_read_b128 v[208:211], v206 offset:22528
	ds_read_b128 v[212:215], v206 offset:23552
	global_load_lds_dwordx4 v[182:183], off
	s_add_i32 m0, s22, 0x2000
	s_add_u32 s22, s26, 0x30000
	v_lshl_add_u64 v[216:217], s[26:27], 0, v[168:169]
	s_addc_u32 s23, s27, 0
	s_add_i32 s50, s51, s36
	global_load_lds_dwordx4 v[216:217], off
	v_lshl_add_u64 v[218:219], s[22:23], 0, v[184:185]
	s_mov_b32 m0, s50
	v_lshl_add_u64 v[220:221], s[30:31], 0, v[170:171]
	global_load_lds_dwordx4 v[218:219], off
	v_lshl_add_u64 v[218:219], s[22:23], 0, v[168:169]
	s_add_i32 m0, s50, 0x2000
	s_nop 0
	global_load_lds_dwordx4 v[218:219], off
	v_lshl_add_u64 v[218:219], s[30:31], 0, v[172:173]
	s_mov_b32 m0, s38
	s_nop 0
	global_load_lds_dwordx4 v[218:219], off
	s_mov_b32 m0, s39
	s_nop 0
	global_load_lds_dwordx4 v[220:221], off
	s_waitcnt vmcnt(8)
	s_waitcnt lgkmcnt(0)
	s_barrier
; #define PG8_STAGE(bufoff, gbase, voff) do { _Pragma("unroll") for (int _i = 0; _i < 2; ++_i) \
;         __builtin_amdgcn_global_load_lds((const unsigned*)((const char*)(gbase) + (voff)[_i]), (LAS unsigned*)(lds + (bufoff) + ldsw + _i * 8192), 16, 0, 0); } while (0)
; #define PG8_LDA(dst, b, h) do { _Pragma("unroll") for (int m = 0; m < 4; ++m) _Pragma("unroll") for (int k = 0; k < 2; ++k) dst[m][k] = *(const LAS bf16x8*)(lds + PG8_SA(b, h) + aoff + m * 2048 + k * 1024); } while (0)
; #define PG8_LDB(dst, b, h) do { _Pragma("unroll") for (int n = 0; n < 2; ++n) _Pragma("unroll") for (int k = 0; k < 2; ++k) dst[n][k] = *(const LAS bf16x8*)(lds + PG8_SB(b, h) + boff + n * 2048 + k * 1024); } while (0)
; #define PG8_MMA(ai, bj, At, Bt) do { __builtin_amdgcn_s_setprio(1); _Pragma("unroll") for (int m = 0; m < 4; ++m) _Pragma("unroll") for (int n = 0; n < 2; ++n) _Pragma("unroll") for (int k = 0; k < 2; ++k) \
;         acc[ai][bj][m][n] = __builtin_amdgcn_mfma_f32_16x16x32_bf16(Bt[n][k], At[m][k], acc[ai][bj][m][n], 0, 0, 0); __builtin_amdgcn_s_setprio(0); } while (0)
; #define PG8_WAIT_V(n) asm volatile("s_waitcnt vmcnt(" #n ")" ::: "memory")
; #define PG8_WAIT_L(n) asm volatile("s_waitcnt lgkmcnt(" #n ")" ::: "memory")
; #define PG8_BAR __builtin_amdgcn_s_barrier()
; #define PG8_SCHED __builtin_amdgcn_sched_barrier(0)
; template <class Epi, class Sched>
; DI void gemm_phase(LAS unsigned char* lds, const int wv, const int lda, const int ldb, const Sched& S, const Epi& E) {
;     ...
;             PG8_WAIT_V(8); PG8_WAIT_L(0); PG8_BAR; PG8_MMA(1, 0, At, B0); PG8_MMA(1, 1, At, B1); PG8_BAR; PG8_SCHED;
;             PG8_LDB(B0, 1, 0); PG8_LDB(B1, 1, 1); PG8_SCHED; PG8_LDA(At, 1, 0); PG8_STAGE(PG8_SA(0, 1), a2 + hstepA, voffA);
;             PG8_WAIT_V(8); PG8_WAIT_L(0); PG8_BAR; PG8_MMA(0, 0, At, B0); PG8_MMA(0, 1, At, B1); PG8_BAR; PG8_SCHED;
	s_waitcnt lgkmcnt(0)
	v_mfma_f32_16x16x32_bf16 v[60:63], v[64:67], v[160:163], v[60:63]
	v_mfma_f32_16x16x32_bf16 v[56:59], v[104:107], v[160:163], v[56:59]
	v_mfma_f32_16x16x32_bf16 v[52:55], v[64:67], v[178:181], v[52:55]
	v_mfma_f32_16x16x32_bf16 v[48:51], v[104:107], v[178:181], v[48:51]
	v_mfma_f32_16x16x32_bf16 v[44:47], v[64:67], v[196:199], v[44:47]
	v_mfma_f32_16x16x32_bf16 v[40:43], v[104:107], v[196:199], v[40:43]
	v_mfma_f32_16x16x32_bf16 v[36:39], v[64:67], v[208:211], v[36:39]
	v_mfma_f32_16x16x32_bf16 v[32:35], v[104:107], v[208:211], v[32:35]
	v_mfma_f32_16x16x32_bf16 v[60:63], v[68:71], v[164:167], v[60:63]
	v_mfma_f32_16x16x32_bf16 v[56:59], v[108:111], v[164:167], v[56:59]
	v_mfma_f32_16x16x32_bf16 v[52:55], v[68:71], v[188:191], v[52:55]
	v_mfma_f32_16x16x32_bf16 v[48:51], v[108:111], v[188:191], v[48:51]
	v_mfma_f32_16x16x32_bf16 v[44:47], v[68:71], v[200:203], v[44:47]
	v_mfma_f32_16x16x32_bf16 v[40:43], v[108:111], v[200:203], v[40:43]
	v_mfma_f32_16x16x32_bf16 v[36:39], v[68:71], v[212:215], v[36:39]
	v_mfma_f32_16x16x32_bf16 v[32:35], v[108:111], v[212:215], v[32:35]
	v_mfma_f32_16x16x32_bf16 v[28:31], v[144:147], v[160:163], v[28:31]
	v_mfma_f32_16x16x32_bf16 v[24:27], v[152:155], v[160:163], v[24:27]
	v_mfma_f32_16x16x32_bf16 v[20:23], v[144:147], v[178:181], v[20:23]
	v_mfma_f32_16x16x32_bf16 v[16:19], v[152:155], v[178:181], v[16:19]
	v_mfma_f32_16x16x32_bf16 v[12:15], v[144:147], v[196:199], v[12:15]
	v_mfma_f32_16x16x32_bf16 v[8:11], v[152:155], v[196:199], v[8:11]
	v_mfma_f32_16x16x32_bf16 v[4:7], v[144:147], v[208:211], v[4:7]
	v_mfma_f32_16x16x32_bf16 v[0:3], v[152:155], v[208:211], v[0:3]
	v_mfma_f32_16x16x32_bf16 v[28:31], v[148:151], v[164:167], v[28:31]
	v_mfma_f32_16x16x32_bf16 v[24:27], v[156:159], v[164:167], v[24:27]
	v_mfma_f32_16x16x32_bf16 v[20:23], v[148:151], v[188:191], v[20:23]
	v_mfma_f32_16x16x32_bf16 v[16:19], v[156:159], v[188:191], v[16:19]
	v_mfma_f32_16x16x32_bf16 v[12:15], v[148:151], v[200:203], v[12:15]
	v_mfma_f32_16x16x32_bf16 v[8:11], v[156:159], v[200:203], v[8:11]
	v_mfma_f32_16x16x32_bf16 v[4:7], v[148:151], v[212:215], v[4:7]
	v_mfma_f32_16x16x32_bf16 v[0:3], v[156:159], v[212:215], v[0:3]
	s_barrier
	s_add_i32 s50, 0, 0x18000
	s_add_i32 s51, 0, 0x1c000
	v_add_u32_e32 v108, s50, v204
	v_add_u32_e32 v156, s51, v204
	ds_read_b128 v[64:67], v108
	ds_read_b128 v[68:71], v108 offset:1024
	ds_read_b128 v[104:107], v108 offset:2048
	ds_read_b128 v[108:111], v108 offset:3072
	ds_read_b128 v[144:147], v156
	ds_read_b128 v[148:151], v156 offset:1024
	ds_read_b128 v[152:155], v156 offset:2048
	ds_read_b128 v[156:159], v156 offset:3072
	s_add_u32 s22, s30, 0x30000
	s_addc_u32 s23, s31, 0
	s_mov_b32 m0, s40
	v_lshl_add_u64 v[222:223], s[22:23], 0, v[172:173]
	ds_read_b128 v[160:163], v206 offset:32768
	ds_read_b128 v[164:167], v206 offset:33792
	ds_read_b128 v[178:181], v206 offset:34816
	ds_read_b128 v[188:191], v206 offset:35840
	ds_read_b128 v[196:199], v206 offset:36864
	ds_read_b128 v[200:203], v206 offset:37888
	ds_read_b128 v[208:211], v206 offset:38912
	ds_read_b128 v[212:215], v206 offset:39936
	global_load_lds_dwordx4 v[222:223], off
	v_lshl_add_u64 v[222:223], s[22:23], 0, v[170:171]
	s_mov_b32 m0, s41
	s_nop 0
	global_load_lds_dwordx4 v[222:223], off
	s_waitcnt vmcnt(8)
	s_waitcnt lgkmcnt(0)
	s_barrier
	s_waitcnt lgkmcnt(0)
	v_mfma_f32_16x16x32_bf16 v[140:143], v[64:67], v[160:163], v[140:143]
	v_mfma_f32_16x16x32_bf16 v[136:139], v[104:107], v[160:163], v[136:139]
	v_mfma_f32_16x16x32_bf16 v[132:135], v[64:67], v[178:181], v[132:135]
	v_mfma_f32_16x16x32_bf16 v[128:131], v[104:107], v[178:181], v[128:131]
	v_mfma_f32_16x16x32_bf16 v[124:127], v[64:67], v[196:199], v[124:127]
	v_mfma_f32_16x16x32_bf16 v[120:123], v[104:107], v[196:199], v[120:123]
	v_mfma_f32_16x16x32_bf16 v[116:119], v[64:67], v[208:211], v[116:119]
	v_mfma_f32_16x16x32_bf16 v[112:115], v[104:107], v[208:211], v[112:115]
	v_mfma_f32_16x16x32_bf16 v[140:143], v[68:71], v[164:167], v[140:143]
	v_mfma_f32_16x16x32_bf16 v[136:139], v[108:111], v[164:167], v[136:139]
	v_mfma_f32_16x16x32_bf16 v[132:135], v[68:71], v[188:191], v[132:135]
	v_mfma_f32_16x16x32_bf16 v[128:131], v[108:111], v[188:191], v[128:131]
	v_mfma_f32_16x16x32_bf16 v[124:127], v[68:71], v[200:203], v[124:127]
	v_mfma_f32_16x16x32_bf16 v[120:123], v[108:111], v[200:203], v[120:123]
	v_mfma_f32_16x16x32_bf16 v[116:119], v[68:71], v[212:215], v[116:119]
	v_mfma_f32_16x16x32_bf16 v[112:115], v[108:111], v[212:215], v[112:115]
	v_mfma_f32_16x16x32_bf16 v[100:103], v[144:147], v[160:163], v[100:103]
	v_mfma_f32_16x16x32_bf16 v[96:99], v[152:155], v[160:163], v[96:99]
	v_mfma_f32_16x16x32_bf16 v[92:95], v[144:147], v[178:181], v[92:95]
	v_mfma_f32_16x16x32_bf16 v[88:91], v[152:155], v[178:181], v[88:91]
	v_mfma_f32_16x16x32_bf16 v[84:87], v[144:147], v[196:199], v[84:87]
	v_mfma_f32_16x16x32_bf16 v[80:83], v[152:155], v[196:199], v[80:83]
	v_mfma_f32_16x16x32_bf16 v[76:79], v[144:147], v[208:211], v[76:79]
	v_mfma_f32_16x16x32_bf16 v[72:75], v[152:155], v[208:211], v[72:75]
	v_mfma_f32_16x16x32_bf16 v[100:103], v[148:151], v[164:167], v[100:103]
	v_mfma_f32_16x16x32_bf16 v[96:99], v[156:159], v[164:167], v[96:99]
	v_mfma_f32_16x16x32_bf16 v[92:95], v[148:151], v[188:191], v[92:95]
	v_mfma_f32_16x16x32_bf16 v[88:91], v[156:159], v[188:191], v[88:91]
	v_mfma_f32_16x16x32_bf16 v[84:87], v[148:151], v[200:203], v[84:87]
	v_mfma_f32_16x16x32_bf16 v[80:83], v[156:159], v[200:203], v[80:83]
	v_mfma_f32_16x16x32_bf16 v[76:79], v[148:151], v[212:215], v[76:79]
	v_mfma_f32_16x16x32_bf16 v[72:75], v[156:159], v[212:215], v[72:75]
	s_barrier
; #define PG8_STAGE(bufoff, gbase, voff) do { _Pragma("unroll") for (int _i = 0; _i < 2; ++_i) \
;         __builtin_amdgcn_global_load_lds((const unsigned*)((const char*)(gbase) + (voff)[_i]), (LAS unsigned*)(lds + (bufoff) + ldsw + _i * 8192), 16, 0, 0); } while (0)
; #define PG8_LDA(dst, b, h) do { _Pragma("unroll") for (int m = 0; m < 4; ++m) _Pragma("unroll") for (int k = 0; k < 2; ++k) dst[m][k] = *(const LAS bf16x8*)(lds + PG8_SA(b, h) + aoff + m * 2048 + k * 1024); } while (0)
; #define PG8_MMA(ai, bj, At, Bt) do { __builtin_amdgcn_s_setprio(1); _Pragma("unroll") for (int m = 0; m < 4; ++m) _Pragma("unroll") for (int n = 0; n < 2; ++n) _Pragma("unroll") for (int k = 0; k < 2; ++k) \
;         acc[ai][bj][m][n] = __builtin_amdgcn_mfma_f32_16x16x32_bf16(Bt[n][k], At[m][k], acc[ai][bj][m][n], 0, 0, 0); __builtin_amdgcn_s_setprio(0); } while (0)
; #define PG8_WAIT_V(n) asm volatile("s_waitcnt vmcnt(" #n ")" ::: "memory")
; #define PG8_WAIT_L(n) asm volatile("s_waitcnt lgkmcnt(" #n ")" ::: "memory")
; #define PG8_BAR __builtin_amdgcn_s_barrier()
; #define PG8_SCHED __builtin_amdgcn_sched_barrier(0)
; template <class Epi, class Sched>
; DI void gemm_phase(LAS unsigned char* lds, const int wv, const int lda, const int ldb, const Sched& S, const Epi& E) {
;     ...
;             PG8_LDA(At, 1, 1); PG8_STAGE(PG8_SB(1, 0), b3, voffB); PG8_STAGE(PG8_SB(1, 1), b3 + hstepB, voffB); PG8_STAGE(PG8_SA(1, 0), a3, voffA);
;             PG8_WAIT_V(8); PG8_WAIT_L(0); PG8_BAR; PG8_MMA(1, 0, At, B0); PG8_MMA(1, 1, At, B1); PG8_BAR; PG8_SCHED;
;         }
;         if (wr == 0) PG8_BAR;
	s_add_i32 s22, s50, s36
	v_lshl_add_u64 v[182:183], v[182:183], 0, s[28:29]
	s_mov_b32 m0, s22
	ds_read_b128 v[160:163], v206 offset:49152
	ds_read_b128 v[164:167], v206 offset:50176
	ds_read_b128 v[178:181], v206 offset:51200
	ds_read_b128 v[188:191], v206 offset:52224
	ds_read_b128 v[196:199], v206 offset:53248
	ds_read_b128 v[200:203], v206 offset:54272
	ds_read_b128 v[208:211], v206 offset:55296
	ds_read_b128 v[212:215], v206 offset:56320
	global_load_lds_dwordx4 v[182:183], off
	s_add_i32 m0, s22, 0x2000
	s_add_u32 s22, s26, 0x30080
	v_lshl_add_u64 v[182:183], v[216:217], 0, s[28:29]
	s_addc_u32 s23, s27, 0
	s_add_i32 s26, s51, s36
	global_load_lds_dwordx4 v[182:183], off
	v_lshl_add_u64 v[182:183], s[22:23], 0, v[184:185]
	s_mov_b32 m0, s26
	s_nop 0
	global_load_lds_dwordx4 v[182:183], off
	v_lshl_add_u64 v[182:183], s[22:23], 0, v[168:169]
	s_add_i32 m0, s26, 0x2000
	s_nop 0
	global_load_lds_dwordx4 v[182:183], off
	v_lshl_add_u64 v[182:183], v[218:219], 0, s[28:29]
	s_mov_b32 m0, s20
	s_nop 0
	global_load_lds_dwordx4 v[182:183], off
	v_lshl_add_u64 v[182:183], v[220:221], 0, s[28:29]
	s_mov_b32 m0, s42
	s_nop 0
	global_load_lds_dwordx4 v[182:183], off
	s_waitcnt vmcnt(8)
	s_waitcnt lgkmcnt(0)
	s_barrier
	s_waitcnt lgkmcnt(0)
	v_mfma_f32_16x16x32_bf16 v[60:63], v[64:67], v[160:163], v[60:63]
	v_mfma_f32_16x16x32_bf16 v[56:59], v[104:107], v[160:163], v[56:59]
	v_mfma_f32_16x16x32_bf16 v[52:55], v[64:67], v[178:181], v[52:55]
	v_mfma_f32_16x16x32_bf16 v[48:51], v[104:107], v[178:181], v[48:51]
	v_mfma_f32_16x16x32_bf16 v[44:47], v[64:67], v[196:199], v[44:47]
	v_mfma_f32_16x16x32_bf16 v[40:43], v[104:107], v[196:199], v[40:43]
	v_mfma_f32_16x16x32_bf16 v[36:39], v[64:67], v[208:211], v[36:39]
	v_mfma_f32_16x16x32_bf16 v[32:35], v[104:107], v[208:211], v[32:35]
	v_mfma_f32_16x16x32_bf16 v[60:63], v[68:71], v[164:167], v[60:63]
	v_mfma_f32_16x16x32_bf16 v[56:59], v[108:111], v[164:167], v[56:59]
	v_mfma_f32_16x16x32_bf16 v[52:55], v[68:71], v[188:191], v[52:55]
	v_mfma_f32_16x16x32_bf16 v[48:51], v[108:111], v[188:191], v[48:51]
	v_mfma_f32_16x16x32_bf16 v[44:47], v[68:71], v[200:203], v[44:47]
	v_mfma_f32_16x16x32_bf16 v[40:43], v[108:111], v[200:203], v[40:43]
	v_mfma_f32_16x16x32_bf16 v[36:39], v[68:71], v[212:215], v[36:39]
	v_mfma_f32_16x16x32_bf16 v[32:35], v[108:111], v[212:215], v[32:35]
	v_mfma_f32_16x16x32_bf16 v[28:31], v[144:147], v[160:163], v[28:31]
	v_mfma_f32_16x16x32_bf16 v[24:27], v[152:155], v[160:163], v[24:27]
	v_mfma_f32_16x16x32_bf16 v[20:23], v[144:147], v[178:181], v[20:23]
	v_mfma_f32_16x16x32_bf16 v[16:19], v[152:155], v[178:181], v[16:19]
	v_mfma_f32_16x16x32_bf16 v[12:15], v[144:147], v[196:199], v[12:15]
	v_mfma_f32_16x16x32_bf16 v[8:11], v[152:155], v[196:199], v[8:11]
	v_mfma_f32_16x16x32_bf16 v[4:7], v[144:147], v[208:211], v[4:7]
	v_mfma_f32_16x16x32_bf16 v[0:3], v[152:155], v[208:211], v[0:3]
	v_mfma_f32_16x16x32_bf16 v[28:31], v[148:151], v[164:167], v[28:31]
	v_mfma_f32_16x16x32_bf16 v[24:27], v[156:159], v[164:167], v[24:27]
	v_mfma_f32_16x16x32_bf16 v[20:23], v[148:151], v[188:191], v[20:23]
	v_mfma_f32_16x16x32_bf16 v[16:19], v[156:159], v[188:191], v[16:19]
	v_mfma_f32_16x16x32_bf16 v[12:15], v[148:151], v[200:203], v[12:15]
	v_mfma_f32_16x16x32_bf16 v[8:11], v[156:159], v[200:203], v[8:11]
	v_mfma_f32_16x16x32_bf16 v[4:7], v[148:151], v[212:215], v[4:7]
	v_mfma_f32_16x16x32_bf16 v[0:3], v[156:159], v[212:215], v[0:3]
	s_barrier
	s_add_i32 s49, s49, 2
	s_add_u32 s0, s0, 0x100
	s_addc_u32 s1, s1, 0
	s_cmp_gt_u32 s49, 9
	s_mov_b64 s[22:23], s[24:25]
	s_cbranch_scc0 .LBB0_1099
	s_and_b64 vcc, exec, s[14:15]
	s_cbranch_vccz .LBB0_1102
	s_barrier

;     DI bool next(int i, Unit& u) const { const long L = (long)i * G + c; if (L >= T.nwg) return false; T.map((int)L, u.pm, u.pn); u.seg = 0; return true; }
;     DI bool next(int i, Unit& u) const { const int ti = i / 3; const long L = (long)ti * G + c; if (L >= T.nwg) return false; T.map((int)L, u.pm, u.pn); u.seg = i - 3 * ti; return true; }
;     DI const char* aptr(const Unit& u) const { return A + (size_t)u.pm * ta + (size_t)kofs(u.seg) * 2; }
;     DI const char* bptr(const Unit& u) const { return B + (size_t)u.pn * tb + (size_t)kofs(u.seg) * 2; }
; #define PG8_STAGE(bufoff, gbase, voff) do { _Pragma("unroll") for (int _i = 0; _i < 2; ++_i) \
;         __builtin_amdgcn_global_load_lds((const unsigned*)((const char*)(gbase) + (voff)[_i]), (LAS unsigned*)(lds + (bufoff) + ldsw + _i * 8192), 16, 0, 0); } while (0)
; #define PG8_LDA(dst, b, h) do { _Pragma("unroll") for (int m = 0; m < 4; ++m) _Pragma("unroll") for (int k = 0; k < 2; ++k) dst[m][k] = *(const LAS bf16x8*)(lds + PG8_SA(b, h) + aoff + m * 2048 + k * 1024); } while (0)
; #define PG8_LDB(dst, b, h) do { _Pragma("unroll") for (int n = 0; n < 2; ++n) _Pragma("unroll") for (int k = 0; k < 2; ++k) dst[n][k] = *(const LAS bf16x8*)(lds + PG8_SB(b, h) + boff + n * 2048 + k * 1024); } while (0)
; #define PG8_BAR __builtin_amdgcn_s_barrier()
; template <class Epi, class Sched>
; DI void gemm_phase(LAS unsigned char* lds, const int wv, const int lda, const int ldb, const Sched& S, const Epi& E) {
;     ...
;         const bool has_next = S.next(ui + 1, nxt);
;         const char* nA = has_next ? S.aptr(nxt) : cA; const char* nB = has_next ? S.bptr(nxt) : cB;
;         for (int t = 0; t < nt; t += 2) {
;             const bool last = (t == nt - 2);
;             const char* a1 = cA + (size_t)(t + 1) * kstep;
;             const char* a2 = last ? nA : cA + (size_t)(t + 2) * kstep; const char* b2 = last ? nB : cB + (size_t)(t + 2) * kstep;
;             const char* a3 = a2 + kstep; const char* b3 = b2 + kstep;
;             PG8_LDB(B0, 0, 0); PG8_LDB(B1, 0, 1); PG8_SCHED; PG8_LDA(At, 0, 0); PG8_STAGE(PG8_SA(1, 1), a1 + hstepA, voffA);
;             PG8_WAIT_V(8); PG8_WAIT_L(0); PG8_BAR; PG8_MMA(0, 0, At, B0); PG8_MMA(0, 1, At, B1); PG8_BAR; PG8_SCHED;
;             PG8_LDA(At, 0, 1); PG8_STAGE(PG8_SB(0, 0), b2, voffB); PG8_STAGE(PG8_SB(0, 1), b2 + hstepB, voffB); PG8_STAGE(PG8_SA(0, 0), a2, voffA);
.LBB0_1299:
	s_add_i32 s54, 0, 0x10000
	s_add_i32 s56, 0, 0x14000
	v_add_u32_e32 v150, s54, v155
	v_add_u32_e32 v172, s56, v155
	ds_read_b128 v[128:131], v150
	ds_read_b128 v[142:145], v150 offset:1024
	ds_read_b128 v[146:149], v150 offset:2048
	ds_read_b128 v[150:153], v150 offset:3072
	ds_read_b128 v[160:163], v172
	ds_read_b128 v[164:167], v172 offset:1024
	ds_read_b128 v[168:171], v172 offset:2048
	ds_read_b128 v[172:175], v172 offset:3072
	v_lshl_add_u64 v[216:217], s[30:31], 0, v[138:139]
	s_add_i32 m0, s27, 0xc000
	ds_read_b128 v[176:179], v159
	ds_read_b128 v[180:183], v159 offset:1024
	ds_read_b128 v[188:191], v159 offset:2048
	ds_read_b128 v[196:199], v159 offset:3072
	ds_read_b128 v[200:203], v159 offset:4096
	ds_read_b128 v[204:207], v159 offset:5120
	ds_read_b128 v[208:211], v159 offset:6144
	ds_read_b128 v[212:215], v159 offset:7168
	global_load_lds_dwordx4 v[216:217], off
	v_lshl_add_u64 v[216:217], s[30:31], 0, v[140:141]
	s_add_i32 m0, s27, 0xe000
	s_nop 0
	global_load_lds_dwordx4 v[216:217], off
	s_add_u32 s34, s30, 0xfff80080
	s_addc_u32 s35, s31, -1
	s_cmp_eq_u32 s53, 28
	s_cselect_b32 s37, s0, s35
	s_cselect_b32 s36, s1, s34
	s_cselect_b32 s35, s11, s52
	s_cselect_b32 s34, s15, s19
	s_waitcnt vmcnt(8)
	s_waitcnt lgkmcnt(0)
	s_barrier
	s_waitcnt lgkmcnt(0)
	v_mfma_f32_16x16x32_bf16 v[124:127], v[128:131], v[176:179], v[124:127]
	v_mfma_f32_16x16x32_bf16 v[120:123], v[146:149], v[176:179], v[120:123]
	v_mfma_f32_16x16x32_bf16 v[108:111], v[128:131], v[188:191], v[108:111]
	v_mfma_f32_16x16x32_bf16 v[104:107], v[146:149], v[188:191], v[104:107]
	v_mfma_f32_16x16x32_bf16 v[96:99], v[128:131], v[200:203], v[96:99]
	v_mfma_f32_16x16x32_bf16 v[88:91], v[146:149], v[200:203], v[88:91]
	v_mfma_f32_16x16x32_bf16 v[80:83], v[128:131], v[208:211], v[80:83]
	v_mfma_f32_16x16x32_bf16 v[72:75], v[146:149], v[208:211], v[72:75]
	v_mfma_f32_16x16x32_bf16 v[124:127], v[142:145], v[180:183], v[124:127]
	v_mfma_f32_16x16x32_bf16 v[120:123], v[150:153], v[180:183], v[120:123]
	v_mfma_f32_16x16x32_bf16 v[108:111], v[142:145], v[196:199], v[108:111]
	v_mfma_f32_16x16x32_bf16 v[104:107], v[150:153], v[196:199], v[104:107]
	v_mfma_f32_16x16x32_bf16 v[96:99], v[142:145], v[204:207], v[96:99]
	v_mfma_f32_16x16x32_bf16 v[88:91], v[150:153], v[204:207], v[88:91]
	v_mfma_f32_16x16x32_bf16 v[80:83], v[142:145], v[212:215], v[80:83]
	v_mfma_f32_16x16x32_bf16 v[72:75], v[150:153], v[212:215], v[72:75]
	v_mfma_f32_16x16x32_bf16 v[116:119], v[160:163], v[176:179], v[116:119]
	v_mfma_f32_16x16x32_bf16 v[112:115], v[168:171], v[176:179], v[112:115]
	v_mfma_f32_16x16x32_bf16 v[100:103], v[160:163], v[188:191], v[100:103]
	v_mfma_f32_16x16x32_bf16 v[92:95], v[168:171], v[188:191], v[92:95]
	v_mfma_f32_16x16x32_bf16 v[84:87], v[160:163], v[200:203], v[84:87]
	v_mfma_f32_16x16x32_bf16 v[76:79], v[168:171], v[200:203], v[76:79]
	v_mfma_f32_16x16x32_bf16 v[68:71], v[160:163], v[208:211], v[68:71]
	v_mfma_f32_16x16x32_bf16 v[64:67], v[168:171], v[208:211], v[64:67]
	v_mfma_f32_16x16x32_bf16 v[116:119], v[164:167], v[180:183], v[116:119]
	v_mfma_f32_16x16x32_bf16 v[112:115], v[172:175], v[180:183], v[112:115]
	v_mfma_f32_16x16x32_bf16 v[100:103], v[164:167], v[196:199], v[100:103]
	v_mfma_f32_16x16x32_bf16 v[92:95], v[172:175], v[196:199], v[92:95]
	v_mfma_f32_16x16x32_bf16 v[84:87], v[164:167], v[204:207], v[84:87]
	v_mfma_f32_16x16x32_bf16 v[76:79], v[172:175], v[204:207], v[76:79]
	v_mfma_f32_16x16x32_bf16 v[68:71], v[164:167], v[212:215], v[68:71]
	v_mfma_f32_16x16x32_bf16 v[64:67], v[172:175], v[212:215], v[64:67]
	s_barrier
	s_add_i32 s54, s54, s41
	v_lshl_add_u64 v[216:217], s[34:35], 0, v[184:185]
	s_mov_b32 m0, s54
	ds_read_b128 v[176:179], v159 offset:16384
	ds_read_b128 v[180:183], v159 offset:17408
	ds_read_b128 v[188:191], v159 offset:18432
	ds_read_b128 v[196:199], v159 offset:19456
	ds_read_b128 v[200:203], v159 offset:20480
	ds_read_b128 v[204:207], v159 offset:21504
	ds_read_b128 v[208:211], v159 offset:22528
	ds_read_b128 v[212:215], v159 offset:23552
	global_load_lds_dwordx4 v[216:217], off
	s_add_i32 m0, s54, 0x2000
	s_add_u32 s54, s34, 0x80000
	v_lshl_add_u64 v[218:219], s[34:35], 0, v[136:137]
	s_addc_u32 s55, s35, 0
	s_add_i32 s56, s56, s41
	global_load_lds_dwordx4 v[218:219], off
	v_lshl_add_u64 v[220:221], s[54:55], 0, v[184:185]
	s_mov_b32 m0, s56
	v_lshl_add_u64 v[222:223], s[36:37], 0, v[134:135]
	global_load_lds_dwordx4 v[220:221], off
	v_lshl_add_u64 v[220:221], s[54:55], 0, v[136:137]
	s_add_i32 m0, s56, 0x2000
	s_nop 0
	global_load_lds_dwordx4 v[220:221], off
	v_lshl_add_u64 v[220:221], s[36:37], 0, v[132:133]
	s_mov_b32 m0, s27
	s_nop 0
	global_load_lds_dwordx4 v[220:221], off
	s_mov_b32 m0, s42
	s_nop 0
	global_load_lds_dwordx4 v[222:223], off
	s_waitcnt vmcnt(8)
	s_waitcnt lgkmcnt(0)
	s_barrier
; #define PG8_STAGE(bufoff, gbase, voff) do { _Pragma("unroll") for (int _i = 0; _i < 2; ++_i) \
;         __builtin_amdgcn_global_load_lds((const unsigned*)((const char*)(gbase) + (voff)[_i]), (LAS unsigned*)(lds + (bufoff) + ldsw + _i * 8192), 16, 0, 0); } while (0)
; #define PG8_LDA(dst, b, h) do { _Pragma("unroll") for (int m = 0; m < 4; ++m) _Pragma("unroll") for (int k = 0; k < 2; ++k) dst[m][k] = *(const LAS bf16x8*)(lds + PG8_SA(b, h) + aoff + m * 2048 + k * 1024); } while (0)
; #define PG8_LDB(dst, b, h) do { _Pragma("unroll") for (int n = 0; n < 2; ++n) _Pragma("unroll") for (int k = 0; k < 2; ++k) dst[n][k] = *(const LAS bf16x8*)(lds + PG8_SB(b, h) + boff + n * 2048 + k * 1024); } while (0)
; #define PG8_MMA(ai, bj, At, Bt) do { __builtin_amdgcn_s_setprio(1); _Pragma("unroll") for (int m = 0; m < 4; ++m) _Pragma("unroll") for (int n = 0; n < 2; ++n) _Pragma("unroll") for (int k = 0; k < 2; ++k) \
;         acc[ai][bj][m][n] = __builtin_amdgcn_mfma_f32_16x16x32_bf16(Bt[n][k], At[m][k], acc[ai][bj][m][n], 0, 0, 0); __builtin_amdgcn_s_setprio(0); } while (0)
; #define PG8_WAIT_V(n) asm volatile("s_waitcnt vmcnt(" #n ")" ::: "memory")
; #define PG8_WAIT_L(n) asm volatile("s_waitcnt lgkmcnt(" #n ")" ::: "memory")
; #define PG8_BAR __builtin_amdgcn_s_barrier()
; #define PG8_SCHED __builtin_amdgcn_sched_barrier(0)
; template <class Epi, class Sched>
; DI void gemm_phase(LAS unsigned char* lds, const int wv, const int lda, const int ldb, const Sched& S, const Epi& E) {
;     ...
;             PG8_WAIT_V(8); PG8_WAIT_L(0); PG8_BAR; PG8_MMA(1, 0, At, B0); PG8_MMA(1, 1, At, B1); PG8_BAR; PG8_SCHED;
;             PG8_LDB(B0, 1, 0); PG8_LDB(B1, 1, 1); PG8_SCHED; PG8_LDA(At, 1, 0); PG8_STAGE(PG8_SA(0, 1), a2 + hstepA, voffA);
;             PG8_WAIT_V(8); PG8_WAIT_L(0); PG8_BAR; PG8_MMA(0, 0, At, B0); PG8_MMA(0, 1, At, B1); PG8_BAR; PG8_SCHED;
	s_waitcnt lgkmcnt(0)
	v_mfma_f32_16x16x32_bf16 v[60:63], v[128:131], v[176:179], v[60:63]
	v_mfma_f32_16x16x32_bf16 v[56:59], v[146:149], v[176:179], v[56:59]
	v_mfma_f32_16x16x32_bf16 v[48:51], v[128:131], v[188:191], v[48:51]
	v_mfma_f32_16x16x32_bf16 v[40:43], v[146:149], v[188:191], v[40:43]
	v_mfma_f32_16x16x32_bf16 v[32:35], v[128:131], v[200:203], v[32:35]
	v_mfma_f32_16x16x32_bf16 v[24:27], v[146:149], v[200:203], v[24:27]
	v_mfma_f32_16x16x32_bf16 v[16:19], v[128:131], v[208:211], v[16:19]
	v_mfma_f32_16x16x32_bf16 v[8:11], v[146:149], v[208:211], v[8:11]
	v_mfma_f32_16x16x32_bf16 v[60:63], v[142:145], v[180:183], v[60:63]
	v_mfma_f32_16x16x32_bf16 v[56:59], v[150:153], v[180:183], v[56:59]
	v_mfma_f32_16x16x32_bf16 v[48:51], v[142:145], v[196:199], v[48:51]
	v_mfma_f32_16x16x32_bf16 v[40:43], v[150:153], v[196:199], v[40:43]
	v_mfma_f32_16x16x32_bf16 v[32:35], v[142:145], v[204:207], v[32:35]
	v_mfma_f32_16x16x32_bf16 v[24:27], v[150:153], v[204:207], v[24:27]
	v_mfma_f32_16x16x32_bf16 v[16:19], v[142:145], v[212:215], v[16:19]
	v_mfma_f32_16x16x32_bf16 v[8:11], v[150:153], v[212:215], v[8:11]
	v_mfma_f32_16x16x32_bf16 v[52:55], v[160:163], v[176:179], v[52:55]
	v_mfma_f32_16x16x32_bf16 v[44:47], v[168:171], v[176:179], v[44:47]
	v_mfma_f32_16x16x32_bf16 v[36:39], v[160:163], v[188:191], v[36:39]
	v_mfma_f32_16x16x32_bf16 v[28:31], v[168:171], v[188:191], v[28:31]
	v_mfma_f32_16x16x32_bf16 v[20:23], v[160:163], v[200:203], v[20:23]
	v_mfma_f32_16x16x32_bf16 v[12:15], v[168:171], v[200:203], v[12:15]
	v_mfma_f32_16x16x32_bf16 v[4:7], v[160:163], v[208:211], v[4:7]
	v_mfma_f32_16x16x32_bf16 v[0:3], v[168:171], v[208:211], v[0:3]
	v_mfma_f32_16x16x32_bf16 v[52:55], v[164:167], v[180:183], v[52:55]
	v_mfma_f32_16x16x32_bf16 v[44:47], v[172:175], v[180:183], v[44:47]
	v_mfma_f32_16x16x32_bf16 v[36:39], v[164:167], v[196:199], v[36:39]
	v_mfma_f32_16x16x32_bf16 v[28:31], v[172:175], v[196:199], v[28:31]
	v_mfma_f32_16x16x32_bf16 v[20:23], v[164:167], v[204:207], v[20:23]
	v_mfma_f32_16x16x32_bf16 v[12:15], v[172:175], v[204:207], v[12:15]
	v_mfma_f32_16x16x32_bf16 v[4:7], v[164:167], v[212:215], v[4:7]
	v_mfma_f32_16x16x32_bf16 v[0:3], v[172:175], v[212:215], v[0:3]
	s_barrier
	s_add_i32 s54, 0, 0x18000
	s_add_i32 s55, 0, 0x1c000
	v_add_u32_e32 v150, s54, v155
	v_add_u32_e32 v172, s55, v155
	ds_read_b128 v[128:131], v150
	ds_read_b128 v[142:145], v150 offset:1024
	ds_read_b128 v[146:149], v150 offset:2048
	ds_read_b128 v[150:153], v150 offset:3072
	ds_read_b128 v[160:163], v172
	ds_read_b128 v[164:167], v172 offset:1024
	ds_read_b128 v[168:171], v172 offset:2048
	ds_read_b128 v[172:175], v172 offset:3072
	s_add_u32 s36, s36, 0x80000
	s_addc_u32 s37, s37, 0
	s_mov_b32 m0, s43
	v_lshl_add_u64 v[234:235], s[36:37], 0, v[132:133]
	ds_read_b128 v[176:179], v159 offset:32768
	ds_read_b128 v[180:183], v159 offset:33792
	ds_read_b128 v[188:191], v159 offset:34816
	ds_read_b128 v[196:199], v159 offset:35840
	ds_read_b128 v[200:203], v159 offset:36864
	ds_read_b128 v[204:207], v159 offset:37888
	ds_read_b128 v[208:211], v159 offset:38912
	ds_read_b128 v[212:215], v159 offset:39936
	global_load_lds_dwordx4 v[234:235], off
	v_lshl_add_u64 v[234:235], s[36:37], 0, v[134:135]
	s_mov_b32 m0, s44
	s_nop 0
	global_load_lds_dwordx4 v[234:235], off
	s_waitcnt vmcnt(8)
	s_waitcnt lgkmcnt(0)
	s_barrier
	s_waitcnt lgkmcnt(0)
	v_mfma_f32_16x16x32_bf16 v[124:127], v[128:131], v[176:179], v[124:127]
	v_mfma_f32_16x16x32_bf16 v[120:123], v[146:149], v[176:179], v[120:123]
	v_mfma_f32_16x16x32_bf16 v[108:111], v[128:131], v[188:191], v[108:111]
	v_mfma_f32_16x16x32_bf16 v[104:107], v[146:149], v[188:191], v[104:107]
	v_mfma_f32_16x16x32_bf16 v[96:99], v[128:131], v[200:203], v[96:99]
	v_mfma_f32_16x16x32_bf16 v[88:91], v[146:149], v[200:203], v[88:91]
	v_mfma_f32_16x16x32_bf16 v[80:83], v[128:131], v[208:211], v[80:83]
	v_mfma_f32_16x16x32_bf16 v[72:75], v[146:149], v[208:211], v[72:75]
	v_mfma_f32_16x16x32_bf16 v[124:127], v[142:145], v[180:183], v[124:127]
	v_mfma_f32_16x16x32_bf16 v[120:123], v[150:153], v[180:183], v[120:123]
	v_mfma_f32_16x16x32_bf16 v[108:111], v[142:145], v[196:199], v[108:111]
	v_mfma_f32_16x16x32_bf16 v[104:107], v[150:153], v[196:199], v[104:107]
	v_mfma_f32_16x16x32_bf16 v[96:99], v[142:145], v[204:207], v[96:99]
	v_mfma_f32_16x16x32_bf16 v[88:91], v[150:153], v[204:207], v[88:91]
	v_mfma_f32_16x16x32_bf16 v[80:83], v[142:145], v[212:215], v[80:83]
	v_mfma_f32_16x16x32_bf16 v[72:75], v[150:153], v[212:215], v[72:75]
	v_mfma_f32_16x16x32_bf16 v[116:119], v[160:163], v[176:179], v[116:119]
	v_mfma_f32_16x16x32_bf16 v[112:115], v[168:171], v[176:179], v[112:115]
	v_mfma_f32_16x16x32_bf16 v[100:103], v[160:163], v[188:191], v[100:103]
	v_mfma_f32_16x16x32_bf16 v[92:95], v[168:171], v[188:191], v[92:95]
	v_mfma_f32_16x16x32_bf16 v[84:87], v[160:163], v[200:203], v[84:87]
	v_mfma_f32_16x16x32_bf16 v[76:79], v[168:171], v[200:203], v[76:79]
	v_mfma_f32_16x16x32_bf16 v[68:71], v[160:163], v[208:211], v[68:71]
	v_mfma_f32_16x16x32_bf16 v[64:67], v[168:171], v[208:211], v[64:67]
	v_mfma_f32_16x16x32_bf16 v[116:119], v[164:167], v[180:183], v[116:119]
	v_mfma_f32_16x16x32_bf16 v[112:115], v[172:175], v[180:183], v[112:115]
	v_mfma_f32_16x16x32_bf16 v[100:103], v[164:167], v[196:199], v[100:103]
	v_mfma_f32_16x16x32_bf16 v[92:95], v[172:175], v[196:199], v[92:95]
	v_mfma_f32_16x16x32_bf16 v[84:87], v[164:167], v[204:207], v[84:87]
	v_mfma_f32_16x16x32_bf16 v[76:79], v[172:175], v[204:207], v[76:79]
	v_mfma_f32_16x16x32_bf16 v[68:71], v[164:167], v[212:215], v[68:71]
	v_mfma_f32_16x16x32_bf16 v[64:67], v[172:175], v[212:215], v[64:67]
	s_barrier
; #define PG8_STAGE(bufoff, gbase, voff) do { _Pragma("unroll") for (int _i = 0; _i < 2; ++_i) \
;         __builtin_amdgcn_global_load_lds((const unsigned*)((const char*)(gbase) + (voff)[_i]), (LAS unsigned*)(lds + (bufoff) + ldsw + _i * 8192), 16, 0, 0); } while (0)
; #define PG8_LDA(dst, b, h) do { _Pragma("unroll") for (int m = 0; m < 4; ++m) _Pragma("unroll") for (int k = 0; k < 2; ++k) dst[m][k] = *(const LAS bf16x8*)(lds + PG8_SA(b, h) + aoff + m * 2048 + k * 1024); } while (0)
; #define PG8_MMA(ai, bj, At, Bt) do { __builtin_amdgcn_s_setprio(1); _Pragma("unroll") for (int m = 0; m < 4; ++m) _Pragma("unroll") for (int n = 0; n < 2; ++n) _Pragma("unroll") for (int k = 0; k < 2; ++k) \
;         acc[ai][bj][m][n] = __builtin_amdgcn_mfma_f32_16x16x32_bf16(Bt[n][k], At[m][k], acc[ai][bj][m][n], 0, 0, 0); __builtin_amdgcn_s_setprio(0); } while (0)
; #define PG8_WAIT_V(n) asm volatile("s_waitcnt vmcnt(" #n ")" ::: "memory")
; #define PG8_WAIT_L(n) asm volatile("s_waitcnt lgkmcnt(" #n ")" ::: "memory")
; #define PG8_BAR __builtin_amdgcn_s_barrier()
; #define PG8_SCHED __builtin_amdgcn_sched_barrier(0)
; template <class Epi, class Sched>
; DI void gemm_phase(LAS unsigned char* lds, const int wv, const int lda, const int ldb, const Sched& S, const Epi& E) {
;     ...
;             PG8_LDA(At, 1, 1); PG8_STAGE(PG8_SB(1, 0), b3, voffB); PG8_STAGE(PG8_SB(1, 1), b3 + hstepB, voffB); PG8_STAGE(PG8_SA(1, 0), a3, voffA);
;             PG8_WAIT_V(8); PG8_WAIT_L(0); PG8_BAR; PG8_MMA(1, 0, At, B0); PG8_MMA(1, 1, At, B1); PG8_BAR; PG8_SCHED;
;         }
;         if (wr == 0) PG8_BAR;
	s_add_i32 s36, s54, s41
	v_lshl_add_u64 v[216:217], v[216:217], 0, s[28:29]
	s_mov_b32 m0, s36
	ds_read_b128 v[176:179], v159 offset:49152
	ds_read_b128 v[180:183], v159 offset:50176
	ds_read_b128 v[188:191], v159 offset:51200
	ds_read_b128 v[196:199], v159 offset:52224
	ds_read_b128 v[200:203], v159 offset:53248
	ds_read_b128 v[204:207], v159 offset:54272
	ds_read_b128 v[208:211], v159 offset:55296
	ds_read_b128 v[212:215], v159 offset:56320
	global_load_lds_dwordx4 v[216:217], off
	s_add_i32 m0, s36, 0x2000
	s_add_u32 s34, s34, 0x80080
	v_lshl_add_u64 v[216:217], v[218:219], 0, s[28:29]
	s_addc_u32 s35, s35, 0
	s_add_i32 s36, s55, s41
	global_load_lds_dwordx4 v[216:217], off
	v_lshl_add_u64 v[216:217], s[34:35], 0, v[184:185]
	s_mov_b32 m0, s36
	s_nop 0
	global_load_lds_dwordx4 v[216:217], off
	v_lshl_add_u64 v[216:217], s[34:35], 0, v[136:137]
	s_add_i32 m0, s36, 0x2000
	s_nop 0
	global_load_lds_dwordx4 v[216:217], off
	v_lshl_add_u64 v[216:217], v[220:221], 0, s[28:29]
	s_mov_b32 m0, s45
	s_nop 0
	global_load_lds_dwordx4 v[216:217], off
	v_lshl_add_u64 v[216:217], v[222:223], 0, s[28:29]
	s_mov_b32 m0, s46
	s_nop 0
	global_load_lds_dwordx4 v[216:217], off
	s_waitcnt vmcnt(8)
	s_waitcnt lgkmcnt(0)
	s_barrier
	s_waitcnt lgkmcnt(0)
	v_mfma_f32_16x16x32_bf16 v[60:63], v[128:131], v[176:179], v[60:63]
	v_mfma_f32_16x16x32_bf16 v[56:59], v[146:149], v[176:179], v[56:59]
	v_mfma_f32_16x16x32_bf16 v[48:51], v[128:131], v[188:191], v[48:51]
	v_mfma_f32_16x16x32_bf16 v[40:43], v[146:149], v[188:191], v[40:43]
	v_mfma_f32_16x16x32_bf16 v[32:35], v[128:131], v[200:203], v[32:35]
	v_mfma_f32_16x16x32_bf16 v[24:27], v[146:149], v[200:203], v[24:27]
	v_mfma_f32_16x16x32_bf16 v[16:19], v[128:131], v[208:211], v[16:19]
	v_mfma_f32_16x16x32_bf16 v[8:11], v[146:149], v[208:211], v[8:11]
	v_mfma_f32_16x16x32_bf16 v[60:63], v[142:145], v[180:183], v[60:63]
	v_mfma_f32_16x16x32_bf16 v[56:59], v[150:153], v[180:183], v[56:59]
	v_mfma_f32_16x16x32_bf16 v[48:51], v[142:145], v[196:199], v[48:51]
	v_mfma_f32_16x16x32_bf16 v[40:43], v[150:153], v[196:199], v[40:43]
	v_mfma_f32_16x16x32_bf16 v[32:35], v[142:145], v[204:207], v[32:35]
	v_mfma_f32_16x16x32_bf16 v[24:27], v[150:153], v[204:207], v[24:27]
	v_mfma_f32_16x16x32_bf16 v[16:19], v[142:145], v[212:215], v[16:19]
	v_mfma_f32_16x16x32_bf16 v[8:11], v[150:153], v[212:215], v[8:11]
	v_mfma_f32_16x16x32_bf16 v[52:55], v[160:163], v[176:179], v[52:55]
	v_mfma_f32_16x16x32_bf16 v[44:47], v[168:171], v[176:179], v[44:47]
	v_mfma_f32_16x16x32_bf16 v[36:39], v[160:163], v[188:191], v[36:39]
	v_mfma_f32_16x16x32_bf16 v[28:31], v[168:171], v[188:191], v[28:31]
	v_mfma_f32_16x16x32_bf16 v[20:23], v[160:163], v[200:203], v[20:23]
	v_mfma_f32_16x16x32_bf16 v[12:15], v[168:171], v[200:203], v[12:15]
	v_mfma_f32_16x16x32_bf16 v[4:7], v[160:163], v[208:211], v[4:7]
	v_mfma_f32_16x16x32_bf16 v[0:3], v[168:171], v[208:211], v[0:3]
	v_mfma_f32_16x16x32_bf16 v[52:55], v[164:167], v[180:183], v[52:55]
	v_mfma_f32_16x16x32_bf16 v[44:47], v[172:175], v[180:183], v[44:47]
	v_mfma_f32_16x16x32_bf16 v[36:39], v[164:167], v[196:199], v[36:39]
	v_mfma_f32_16x16x32_bf16 v[28:31], v[172:175], v[196:199], v[28:31]
	v_mfma_f32_16x16x32_bf16 v[20:23], v[164:167], v[204:207], v[20:23]
	v_mfma_f32_16x16x32_bf16 v[12:15], v[172:175], v[204:207], v[12:15]
	v_mfma_f32_16x16x32_bf16 v[4:7], v[164:167], v[212:215], v[4:7]
	v_mfma_f32_16x16x32_bf16 v[0:3], v[172:175], v[212:215], v[0:3]
	s_barrier
	s_add_i32 s53, s53, 2
	s_add_u32 s30, s30, 0x100
	s_addc_u32 s31, s31, 0
	s_add_u32 s19, s19, 0x100
	s_addc_u32 s52, s52, 0
	s_cmp_gt_u32 s53, 29
	s_cbranch_scc0 .LBB0_1299
	s_and_b64 vcc, exec, s[12:13]
	s_cbranch_vccz .LBB0_1302
	s_barrier

;     DI bool next(int i, Unit& u) const { const long L = (long)i * G + c; if (L >= T.nwg) return false; T.map((int)L, u.pm, u.pn); u.seg = 0; return true; }
;     DI bool next(int i, Unit& u) const { const int ti = i / 3; const long L = (long)ti * G + c; if (L >= T.nwg) return false; T.map((int)L, u.pm, u.pn); u.seg = i - 3 * ti; return true; }
;     DI const char* aptr(const Unit& u) const { return A + (size_t)u.pm * ta + (size_t)kofs(u.seg) * 2; }
;     DI const char* bptr(const Unit& u) const { return B + (size_t)u.pn * tb + (size_t)kofs(u.seg) * 2; }
; #define PG8_STAGE(bufoff, gbase, voff) do { _Pragma("unroll") for (int _i = 0; _i < 2; ++_i) \
;         __builtin_amdgcn_global_load_lds((const unsigned*)((const char*)(gbase) + (voff)[_i]), (LAS unsigned*)(lds + (bufoff) + ldsw + _i * 8192), 16, 0, 0); } while (0)
; #define PG8_LDA(dst, b, h) do { _Pragma("unroll") for (int m = 0; m < 4; ++m) _Pragma("unroll") for (int k = 0; k < 2; ++k) dst[m][k] = *(const LAS bf16x8*)(lds + PG8_SA(b, h) + aoff + m * 2048 + k * 1024); } while (0)
; #define PG8_LDB(dst, b, h) do { _Pragma("unroll") for (int n = 0; n < 2; ++n) _Pragma("unroll") for (int k = 0; k < 2; ++k) dst[n][k] = *(const LAS bf16x8*)(lds + PG8_SB(b, h) + boff + n * 2048 + k * 1024); } while (0)
; #define PG8_BAR __builtin_amdgcn_s_barrier()
; template <class Epi, class Sched>
; DI void gemm_phase(LAS unsigned char* lds, const int wv, const int lda, const int ldb, const Sched& S, const Epi& E) {
;     ...
;         const bool has_next = S.next(ui + 1, nxt);
;         const char* nA = has_next ? S.aptr(nxt) : cA; const char* nB = has_next ? S.bptr(nxt) : cB;
;         for (int t = 0; t < nt; t += 2) {
;             const bool last = (t == nt - 2);
;             const char* a1 = cA + (size_t)(t + 1) * kstep;
;             const char* a2 = last ? nA : cA + (size_t)(t + 2) * kstep; const char* b2 = last ? nB : cB + (size_t)(t + 2) * kstep;
;             const char* a3 = a2 + kstep; const char* b3 = b2 + kstep;
;             PG8_LDB(B0, 0, 0); PG8_LDB(B1, 0, 1); PG8_SCHED; PG8_LDA(At, 0, 0); PG8_STAGE(PG8_SA(1, 1), a1 + hstepA, voffA);
;             PG8_WAIT_V(8); PG8_WAIT_L(0); PG8_BAR; PG8_MMA(0, 0, At, B0); PG8_MMA(0, 1, At, B1); PG8_BAR; PG8_SCHED;
;             PG8_LDA(At, 0, 1); PG8_STAGE(PG8_SB(0, 0), b2, voffB); PG8_STAGE(PG8_SB(0, 1), b2 + hstepB, voffB); PG8_STAGE(PG8_SA(0, 0), a2, voffA);
.LBB0_1397:
	s_add_i32 s51, 0, 0x10000
	v_add_u32_e32 v142, s51, v145
	s_add_i32 s54, 0, 0x14000
	ds_read_b128 v[138:141], v142
	ds_read_b128 v[148:151], v142 offset:1024
	ds_read_b128 v[152:155], v142 offset:2048
	ds_read_b128 v[156:159], v142 offset:3072
	v_add_u32_e32 v142, s54, v145
	ds_read_b128 v[160:163], v142
	ds_read_b128 v[164:167], v142 offset:1024
	ds_read_b128 v[168:171], v142 offset:2048
	ds_read_b128 v[172:175], v142 offset:3072
	v_lshl_add_u64 v[142:143], s[26:27], 0, v[134:135]
	s_add_i32 m0, s25, 0xc000
	ds_read_b128 v[176:179], v147
	ds_read_b128 v[180:183], v147 offset:1024
	ds_read_b128 v[188:191], v147 offset:2048
	ds_read_b128 v[196:199], v147 offset:3072
	ds_read_b128 v[200:203], v147 offset:4096
	ds_read_b128 v[204:207], v147 offset:5120
	ds_read_b128 v[208:211], v147 offset:6144
	ds_read_b128 v[212:215], v147 offset:7168
	global_load_lds_dwordx4 v[142:143], off
	v_lshl_add_u64 v[142:143], s[26:27], 0, v[136:137]
	s_add_i32 m0, s25, 0xe000
	s_nop 0
	global_load_lds_dwordx4 v[142:143], off
	s_add_u32 s30, s26, 0xfff80080
	s_addc_u32 s31, s27, -1
	s_cmp_eq_u32 s50, 28
	s_cselect_b32 s35, s0, s31
	s_cselect_b32 s34, s1, s30
	s_cselect_b32 s31, s13, s49
	s_cselect_b32 s30, s15, s48
	s_waitcnt vmcnt(8)
	s_waitcnt lgkmcnt(0)
	s_barrier
	s_waitcnt lgkmcnt(0)
	v_mfma_f32_16x16x32_bf16 v[124:127], v[138:141], v[176:179], v[124:127]
	v_mfma_f32_16x16x32_bf16 v[120:123], v[152:155], v[176:179], v[120:123]
	v_mfma_f32_16x16x32_bf16 v[108:111], v[138:141], v[188:191], v[108:111]
	v_mfma_f32_16x16x32_bf16 v[104:107], v[152:155], v[188:191], v[104:107]
	v_mfma_f32_16x16x32_bf16 v[92:95], v[138:141], v[200:203], v[92:95]
	v_mfma_f32_16x16x32_bf16 v[88:91], v[152:155], v[200:203], v[88:91]
	v_mfma_f32_16x16x32_bf16 v[76:79], v[138:141], v[208:211], v[76:79]
	v_mfma_f32_16x16x32_bf16 v[72:75], v[152:155], v[208:211], v[72:75]
	v_mfma_f32_16x16x32_bf16 v[124:127], v[148:151], v[180:183], v[124:127]
	v_mfma_f32_16x16x32_bf16 v[120:123], v[156:159], v[180:183], v[120:123]
	v_mfma_f32_16x16x32_bf16 v[108:111], v[148:151], v[196:199], v[108:111]
	v_mfma_f32_16x16x32_bf16 v[104:107], v[156:159], v[196:199], v[104:107]
	v_mfma_f32_16x16x32_bf16 v[92:95], v[148:151], v[204:207], v[92:95]
	v_mfma_f32_16x16x32_bf16 v[88:91], v[156:159], v[204:207], v[88:91]
	v_mfma_f32_16x16x32_bf16 v[76:79], v[148:151], v[212:215], v[76:79]
	v_mfma_f32_16x16x32_bf16 v[72:75], v[156:159], v[212:215], v[72:75]
	v_mfma_f32_16x16x32_bf16 v[116:119], v[160:163], v[176:179], v[116:119]
	v_mfma_f32_16x16x32_bf16 v[112:115], v[168:171], v[176:179], v[112:115]
	v_mfma_f32_16x16x32_bf16 v[100:103], v[160:163], v[188:191], v[100:103]
	v_mfma_f32_16x16x32_bf16 v[96:99], v[168:171], v[188:191], v[96:99]
	v_mfma_f32_16x16x32_bf16 v[84:87], v[160:163], v[200:203], v[84:87]
	v_mfma_f32_16x16x32_bf16 v[80:83], v[168:171], v[200:203], v[80:83]
	v_mfma_f32_16x16x32_bf16 v[68:71], v[160:163], v[208:211], v[68:71]
	v_mfma_f32_16x16x32_bf16 v[64:67], v[168:171], v[208:211], v[64:67]
	v_mfma_f32_16x16x32_bf16 v[116:119], v[164:167], v[180:183], v[116:119]
	v_mfma_f32_16x16x32_bf16 v[112:115], v[172:175], v[180:183], v[112:115]
	v_mfma_f32_16x16x32_bf16 v[100:103], v[164:167], v[196:199], v[100:103]
	v_mfma_f32_16x16x32_bf16 v[96:99], v[172:175], v[196:199], v[96:99]
	v_mfma_f32_16x16x32_bf16 v[84:87], v[164:167], v[204:207], v[84:87]
	v_mfma_f32_16x16x32_bf16 v[80:83], v[172:175], v[204:207], v[80:83]
	v_mfma_f32_16x16x32_bf16 v[68:71], v[164:167], v[212:215], v[68:71]
	v_mfma_f32_16x16x32_bf16 v[64:67], v[172:175], v[212:215], v[64:67]
	s_barrier
	s_add_i32 s51, s51, s38
	v_lshl_add_u64 v[142:143], s[30:31], 0, v[184:185]
	s_mov_b32 m0, s51
	ds_read_b128 v[176:179], v147 offset:16384
	ds_read_b128 v[180:183], v147 offset:17408
	ds_read_b128 v[188:191], v147 offset:18432
	ds_read_b128 v[196:199], v147 offset:19456
	ds_read_b128 v[200:203], v147 offset:20480
	ds_read_b128 v[204:207], v147 offset:21504
	ds_read_b128 v[208:211], v147 offset:22528
	ds_read_b128 v[212:215], v147 offset:23552
	global_load_lds_dwordx4 v[142:143], off
	s_add_i32 m0, s51, 0x2000
	s_add_u32 s52, s30, 0x80000
	v_lshl_add_u64 v[216:217], s[30:31], 0, v[132:133]
	s_addc_u32 s53, s31, 0
	s_add_i32 s51, s54, s38
	global_load_lds_dwordx4 v[216:217], off
	v_lshl_add_u64 v[218:219], s[52:53], 0, v[184:185]
	s_mov_b32 m0, s51
	v_lshl_add_u64 v[220:221], s[34:35], 0, v[130:131]
	global_load_lds_dwordx4 v[218:219], off
	v_lshl_add_u64 v[218:219], s[52:53], 0, v[132:133]
	s_add_i32 m0, s51, 0x2000
	s_nop 0
	global_load_lds_dwordx4 v[218:219], off
	v_lshl_add_u64 v[218:219], s[34:35], 0, v[128:129]
	s_mov_b32 m0, s25
	s_nop 0
	global_load_lds_dwordx4 v[218:219], off
	s_mov_b32 m0, s39
	s_nop 0
	global_load_lds_dwordx4 v[220:221], off
	s_waitcnt vmcnt(8)
	s_waitcnt lgkmcnt(0)
	s_barrier
; #define PG8_STAGE(bufoff, gbase, voff) do { _Pragma("unroll") for (int _i = 0; _i < 2; ++_i) \
;         __builtin_amdgcn_global_load_lds((const unsigned*)((const char*)(gbase) + (voff)[_i]), (LAS unsigned*)(lds + (bufoff) + ldsw + _i * 8192), 16, 0, 0); } while (0)
; #define PG8_LDA(dst, b, h) do { _Pragma("unroll") for (int m = 0; m < 4; ++m) _Pragma("unroll") for (int k = 0; k < 2; ++k) dst[m][k] = *(const LAS bf16x8*)(lds + PG8_SA(b, h) + aoff + m * 2048 + k * 1024); } while (0)
; #define PG8_LDB(dst, b, h) do { _Pragma("unroll") for (int n = 0; n < 2; ++n) _Pragma("unroll") for (int k = 0; k < 2; ++k) dst[n][k] = *(const LAS bf16x8*)(lds + PG8_SB(b, h) + boff + n * 2048 + k * 1024); } while (0)
; #define PG8_MMA(ai, bj, At, Bt) do { __builtin_amdgcn_s_setprio(1); _Pragma("unroll") for (int m = 0; m < 4; ++m) _Pragma("unroll") for (int n = 0; n < 2; ++n) _Pragma("unroll") for (int k = 0; k < 2; ++k) \
;         acc[ai][bj][m][n] = __builtin_amdgcn_mfma_f32_16x16x32_bf16(Bt[n][k], At[m][k], acc[ai][bj][m][n], 0, 0, 0); __builtin_amdgcn_s_setprio(0); } while (0)
; #define PG8_WAIT_V(n) asm volatile("s_waitcnt vmcnt(" #n ")" ::: "memory")
; #define PG8_WAIT_L(n) asm volatile("s_waitcnt lgkmcnt(" #n ")" ::: "memory")
; #define PG8_BAR __builtin_amdgcn_s_barrier()
; #define PG8_SCHED __builtin_amdgcn_sched_barrier(0)
; template <class Epi, class Sched>
; DI void gemm_phase(LAS unsigned char* lds, const int wv, const int lda, const int ldb, const Sched& S, const Epi& E) {
;     ...
;             PG8_WAIT_V(8); PG8_WAIT_L(0); PG8_BAR; PG8_MMA(1, 0, At, B0); PG8_MMA(1, 1, At, B1); PG8_BAR; PG8_SCHED;
;             PG8_LDB(B0, 1, 0); PG8_LDB(B1, 1, 1); PG8_SCHED; PG8_LDA(At, 1, 0); PG8_STAGE(PG8_SA(0, 1), a2 + hstepA, voffA);
;             PG8_WAIT_V(8); PG8_WAIT_L(0); PG8_BAR; PG8_MMA(0, 0, At, B0); PG8_MMA(0, 1, At, B1); PG8_BAR; PG8_SCHED;
	s_waitcnt lgkmcnt(0)
	v_mfma_f32_16x16x32_bf16 v[60:63], v[138:141], v[176:179], v[60:63]
	v_mfma_f32_16x16x32_bf16 v[56:59], v[152:155], v[176:179], v[56:59]
	v_mfma_f32_16x16x32_bf16 v[44:47], v[138:141], v[188:191], v[44:47]
	v_mfma_f32_16x16x32_bf16 v[40:43], v[152:155], v[188:191], v[40:43]
	v_mfma_f32_16x16x32_bf16 v[28:31], v[138:141], v[200:203], v[28:31]
	v_mfma_f32_16x16x32_bf16 v[24:27], v[152:155], v[200:203], v[24:27]
	v_mfma_f32_16x16x32_bf16 v[12:15], v[138:141], v[208:211], v[12:15]
	v_mfma_f32_16x16x32_bf16 v[8:11], v[152:155], v[208:211], v[8:11]
	v_mfma_f32_16x16x32_bf16 v[60:63], v[148:151], v[180:183], v[60:63]
	v_mfma_f32_16x16x32_bf16 v[56:59], v[156:159], v[180:183], v[56:59]
	v_mfma_f32_16x16x32_bf16 v[44:47], v[148:151], v[196:199], v[44:47]
	v_mfma_f32_16x16x32_bf16 v[40:43], v[156:159], v[196:199], v[40:43]
	v_mfma_f32_16x16x32_bf16 v[28:31], v[148:151], v[204:207], v[28:31]
	v_mfma_f32_16x16x32_bf16 v[24:27], v[156:159], v[204:207], v[24:27]
	v_mfma_f32_16x16x32_bf16 v[12:15], v[148:151], v[212:215], v[12:15]
	v_mfma_f32_16x16x32_bf16 v[8:11], v[156:159], v[212:215], v[8:11]
	v_mfma_f32_16x16x32_bf16 v[52:55], v[160:163], v[176:179], v[52:55]
	v_mfma_f32_16x16x32_bf16 v[48:51], v[168:171], v[176:179], v[48:51]
	v_mfma_f32_16x16x32_bf16 v[36:39], v[160:163], v[188:191], v[36:39]
	v_mfma_f32_16x16x32_bf16 v[32:35], v[168:171], v[188:191], v[32:35]
	v_mfma_f32_16x16x32_bf16 v[20:23], v[160:163], v[200:203], v[20:23]
	v_mfma_f32_16x16x32_bf16 v[16:19], v[168:171], v[200:203], v[16:19]
	v_mfma_f32_16x16x32_bf16 v[4:7], v[160:163], v[208:211], v[4:7]
	v_mfma_f32_16x16x32_bf16 v[0:3], v[168:171], v[208:211], v[0:3]
	v_mfma_f32_16x16x32_bf16 v[52:55], v[164:167], v[180:183], v[52:55]
	v_mfma_f32_16x16x32_bf16 v[48:51], v[172:175], v[180:183], v[48:51]
	v_mfma_f32_16x16x32_bf16 v[36:39], v[164:167], v[196:199], v[36:39]
	v_mfma_f32_16x16x32_bf16 v[32:35], v[172:175], v[196:199], v[32:35]
	v_mfma_f32_16x16x32_bf16 v[20:23], v[164:167], v[204:207], v[20:23]
	v_mfma_f32_16x16x32_bf16 v[16:19], v[172:175], v[204:207], v[16:19]
	v_mfma_f32_16x16x32_bf16 v[4:7], v[164:167], v[212:215], v[4:7]
	v_mfma_f32_16x16x32_bf16 v[0:3], v[172:175], v[212:215], v[0:3]
	s_barrier
	s_add_i32 s51, 0, 0x18000
	s_add_i32 s52, 0, 0x1c000
	v_add_u32_e32 v156, s51, v145
	v_add_u32_e32 v172, s52, v145
	ds_read_b128 v[138:141], v156
	ds_read_b128 v[148:151], v156 offset:1024
	ds_read_b128 v[152:155], v156 offset:2048
	ds_read_b128 v[156:159], v156 offset:3072
	ds_read_b128 v[160:163], v172
	ds_read_b128 v[164:167], v172 offset:1024
	ds_read_b128 v[168:171], v172 offset:2048
	ds_read_b128 v[172:175], v172 offset:3072
	s_add_u32 s34, s34, 0x80000
	s_addc_u32 s35, s35, 0
	s_mov_b32 m0, s40
	v_lshl_add_u64 v[222:223], s[34:35], 0, v[128:129]
	ds_read_b128 v[176:179], v147 offset:32768
	ds_read_b128 v[180:183], v147 offset:33792
	ds_read_b128 v[188:191], v147 offset:34816
	ds_read_b128 v[196:199], v147 offset:35840
	ds_read_b128 v[200:203], v147 offset:36864
	ds_read_b128 v[204:207], v147 offset:37888
	ds_read_b128 v[208:211], v147 offset:38912
	ds_read_b128 v[212:215], v147 offset:39936
	global_load_lds_dwordx4 v[222:223], off
	v_lshl_add_u64 v[222:223], s[34:35], 0, v[130:131]
	s_mov_b32 m0, s41
	s_nop 0
	global_load_lds_dwordx4 v[222:223], off
	s_waitcnt vmcnt(8)
	s_waitcnt lgkmcnt(0)
	s_barrier
	s_waitcnt lgkmcnt(0)
	v_mfma_f32_16x16x32_bf16 v[124:127], v[138:141], v[176:179], v[124:127]
	v_mfma_f32_16x16x32_bf16 v[120:123], v[152:155], v[176:179], v[120:123]
	v_mfma_f32_16x16x32_bf16 v[108:111], v[138:141], v[188:191], v[108:111]
	v_mfma_f32_16x16x32_bf16 v[104:107], v[152:155], v[188:191], v[104:107]
	v_mfma_f32_16x16x32_bf16 v[92:95], v[138:141], v[200:203], v[92:95]
	v_mfma_f32_16x16x32_bf16 v[88:91], v[152:155], v[200:203], v[88:91]
	v_mfma_f32_16x16x32_bf16 v[76:79], v[138:141], v[208:211], v[76:79]
	v_mfma_f32_16x16x32_bf16 v[72:75], v[152:155], v[208:211], v[72:75]
	v_mfma_f32_16x16x32_bf16 v[124:127], v[148:151], v[180:183], v[124:127]
	v_mfma_f32_16x16x32_bf16 v[120:123], v[156:159], v[180:183], v[120:123]
	v_mfma_f32_16x16x32_bf16 v[108:111], v[148:151], v[196:199], v[108:111]
	v_mfma_f32_16x16x32_bf16 v[104:107], v[156:159], v[196:199], v[104:107]
	v_mfma_f32_16x16x32_bf16 v[92:95], v[148:151], v[204:207], v[92:95]
	v_mfma_f32_16x16x32_bf16 v[88:91], v[156:159], v[204:207], v[88:91]
	v_mfma_f32_16x16x32_bf16 v[76:79], v[148:151], v[212:215], v[76:79]
	v_mfma_f32_16x16x32_bf16 v[72:75], v[156:159], v[212:215], v[72:75]
	v_mfma_f32_16x16x32_bf16 v[116:119], v[160:163], v[176:179], v[116:119]
	v_mfma_f32_16x16x32_bf16 v[112:115], v[168:171], v[176:179], v[112:115]
	v_mfma_f32_16x16x32_bf16 v[100:103], v[160:163], v[188:191], v[100:103]
	v_mfma_f32_16x16x32_bf16 v[96:99], v[168:171], v[188:191], v[96:99]
	v_mfma_f32_16x16x32_bf16 v[84:87], v[160:163], v[200:203], v[84:87]
	v_mfma_f32_16x16x32_bf16 v[80:83], v[168:171], v[200:203], v[80:83]
	v_mfma_f32_16x16x32_bf16 v[68:71], v[160:163], v[208:211], v[68:71]
	v_mfma_f32_16x16x32_bf16 v[64:67], v[168:171], v[208:211], v[64:67]
	v_mfma_f32_16x16x32_bf16 v[116:119], v[164:167], v[180:183], v[116:119]
	v_mfma_f32_16x16x32_bf16 v[112:115], v[172:175], v[180:183], v[112:115]
	v_mfma_f32_16x16x32_bf16 v[100:103], v[164:167], v[196:199], v[100:103]
	v_mfma_f32_16x16x32_bf16 v[96:99], v[172:175], v[196:199], v[96:99]
	v_mfma_f32_16x16x32_bf16 v[84:87], v[164:167], v[204:207], v[84:87]
	v_mfma_f32_16x16x32_bf16 v[80:83], v[172:175], v[204:207], v[80:83]
	v_mfma_f32_16x16x32_bf16 v[68:71], v[164:167], v[212:215], v[68:71]
	v_mfma_f32_16x16x32_bf16 v[64:67], v[172:175], v[212:215], v[64:67]
	s_barrier
; #define PG8_STAGE(bufoff, gbase, voff) do { _Pragma("unroll") for (int _i = 0; _i < 2; ++_i) \
;         __builtin_amdgcn_global_load_lds((const unsigned*)((const char*)(gbase) + (voff)[_i]), (LAS unsigned*)(lds + (bufoff) + ldsw + _i * 8192), 16, 0, 0); } while (0)
; #define PG8_LDA(dst, b, h) do { _Pragma("unroll") for (int m = 0; m < 4; ++m) _Pragma("unroll") for (int k = 0; k < 2; ++k) dst[m][k] = *(const LAS bf16x8*)(lds + PG8_SA(b, h) + aoff + m * 2048 + k * 1024); } while (0)
; #define PG8_MMA(ai, bj, At, Bt) do { __builtin_amdgcn_s_setprio(1); _Pragma("unroll") for (int m = 0; m < 4; ++m) _Pragma("unroll") for (int n = 0; n < 2; ++n) _Pragma("unroll") for (int k = 0; k < 2; ++k) \
;         acc[ai][bj][m][n] = __builtin_amdgcn_mfma_f32_16x16x32_bf16(Bt[n][k], At[m][k], acc[ai][bj][m][n], 0, 0, 0); __builtin_amdgcn_s_setprio(0); } while (0)
; #define PG8_WAIT_V(n) asm volatile("s_waitcnt vmcnt(" #n ")" ::: "memory")
; #define PG8_WAIT_L(n) asm volatile("s_waitcnt lgkmcnt(" #n ")" ::: "memory")
; #define PG8_BAR __builtin_amdgcn_s_barrier()
; #define PG8_SCHED __builtin_amdgcn_sched_barrier(0)
; template <class Epi, class Sched>
; DI void gemm_phase(LAS unsigned char* lds, const int wv, const int lda, const int ldb, const Sched& S, const Epi& E) {
;     ...
;             PG8_LDA(At, 1, 1); PG8_STAGE(PG8_SB(1, 0), b3, voffB); PG8_STAGE(PG8_SB(1, 1), b3 + hstepB, voffB); PG8_STAGE(PG8_SA(1, 0), a3, voffA);
;             PG8_WAIT_V(8); PG8_WAIT_L(0); PG8_BAR; PG8_MMA(1, 0, At, B0); PG8_MMA(1, 1, At, B1); PG8_BAR; PG8_SCHED;
;         }
;         if (wr == 0) PG8_BAR;
	s_add_i32 s34, s51, s38
	v_lshl_add_u64 v[142:143], v[142:143], 0, s[28:29]
	s_mov_b32 m0, s34
	ds_read_b128 v[176:179], v147 offset:49152
	ds_read_b128 v[180:183], v147 offset:50176
	ds_read_b128 v[188:191], v147 offset:51200
	ds_read_b128 v[196:199], v147 offset:52224
	ds_read_b128 v[200:203], v147 offset:53248
	ds_read_b128 v[204:207], v147 offset:54272
	ds_read_b128 v[208:211], v147 offset:55296
	ds_read_b128 v[212:215], v147 offset:56320
	global_load_lds_dwordx4 v[142:143], off
	s_add_i32 m0, s34, 0x2000
	s_add_u32 s30, s30, 0x80080
	v_lshl_add_u64 v[142:143], v[216:217], 0, s[28:29]
	s_addc_u32 s31, s31, 0
	s_add_i32 s34, s52, s38
	global_load_lds_dwordx4 v[142:143], off
	v_lshl_add_u64 v[142:143], s[30:31], 0, v[184:185]
	s_mov_b32 m0, s34
	s_nop 0
	global_load_lds_dwordx4 v[142:143], off
	v_lshl_add_u64 v[142:143], s[30:31], 0, v[132:133]
	s_add_i32 m0, s34, 0x2000
	s_nop 0
	global_load_lds_dwordx4 v[142:143], off
	v_lshl_add_u64 v[142:143], v[218:219], 0, s[28:29]
	s_mov_b32 m0, s43
	s_nop 0
	global_load_lds_dwordx4 v[142:143], off
	v_lshl_add_u64 v[142:143], v[220:221], 0, s[28:29]
	s_mov_b32 m0, s44
	s_nop 0
	global_load_lds_dwordx4 v[142:143], off
	s_waitcnt vmcnt(8)
	s_waitcnt lgkmcnt(0)
	s_barrier
	s_waitcnt lgkmcnt(0)
	v_mfma_f32_16x16x32_bf16 v[60:63], v[138:141], v[176:179], v[60:63]
	v_mfma_f32_16x16x32_bf16 v[56:59], v[152:155], v[176:179], v[56:59]
	v_mfma_f32_16x16x32_bf16 v[44:47], v[138:141], v[188:191], v[44:47]
	v_mfma_f32_16x16x32_bf16 v[40:43], v[152:155], v[188:191], v[40:43]
	v_mfma_f32_16x16x32_bf16 v[28:31], v[138:141], v[200:203], v[28:31]
	v_mfma_f32_16x16x32_bf16 v[24:27], v[152:155], v[200:203], v[24:27]
	v_mfma_f32_16x16x32_bf16 v[12:15], v[138:141], v[208:211], v[12:15]
	v_mfma_f32_16x16x32_bf16 v[8:11], v[152:155], v[208:211], v[8:11]
	v_mfma_f32_16x16x32_bf16 v[60:63], v[148:151], v[180:183], v[60:63]
	v_mfma_f32_16x16x32_bf16 v[56:59], v[156:159], v[180:183], v[56:59]
	v_mfma_f32_16x16x32_bf16 v[44:47], v[148:151], v[196:199], v[44:47]
	v_mfma_f32_16x16x32_bf16 v[40:43], v[156:159], v[196:199], v[40:43]
	v_mfma_f32_16x16x32_bf16 v[28:31], v[148:151], v[204:207], v[28:31]
	v_mfma_f32_16x16x32_bf16 v[24:27], v[156:159], v[204:207], v[24:27]
	v_mfma_f32_16x16x32_bf16 v[12:15], v[148:151], v[212:215], v[12:15]
	v_mfma_f32_16x16x32_bf16 v[8:11], v[156:159], v[212:215], v[8:11]
	v_mfma_f32_16x16x32_bf16 v[52:55], v[160:163], v[176:179], v[52:55]
	v_mfma_f32_16x16x32_bf16 v[48:51], v[168:171], v[176:179], v[48:51]
	v_mfma_f32_16x16x32_bf16 v[36:39], v[160:163], v[188:191], v[36:39]
	v_mfma_f32_16x16x32_bf16 v[32:35], v[168:171], v[188:191], v[32:35]
	v_mfma_f32_16x16x32_bf16 v[20:23], v[160:163], v[200:203], v[20:23]
	v_mfma_f32_16x16x32_bf16 v[16:19], v[168:171], v[200:203], v[16:19]
	v_mfma_f32_16x16x32_bf16 v[4:7], v[160:163], v[208:211], v[4:7]
	v_mfma_f32_16x16x32_bf16 v[0:3], v[168:171], v[208:211], v[0:3]
	v_mfma_f32_16x16x32_bf16 v[52:55], v[164:167], v[180:183], v[52:55]
	v_mfma_f32_16x16x32_bf16 v[48:51], v[172:175], v[180:183], v[48:51]
	v_mfma_f32_16x16x32_bf16 v[36:39], v[164:167], v[196:199], v[36:39]
	v_mfma_f32_16x16x32_bf16 v[32:35], v[172:175], v[196:199], v[32:35]
	v_mfma_f32_16x16x32_bf16 v[20:23], v[164:167], v[204:207], v[20:23]
	v_mfma_f32_16x16x32_bf16 v[16:19], v[172:175], v[204:207], v[16:19]
	v_mfma_f32_16x16x32_bf16 v[4:7], v[164:167], v[212:215], v[4:7]
	v_mfma_f32_16x16x32_bf16 v[0:3], v[172:175], v[212:215], v[0:3]
	s_barrier
	s_add_i32 s50, s50, 2
	s_add_u32 s26, s26, 0x100
	s_addc_u32 s27, s27, 0
	s_add_u32 s48, s48, 0x100
	s_addc_u32 s49, s49, 0
	s_cmp_gt_u32 s50, 29
	s_cbranch_scc0 .LBB0_1397
	s_and_b64 vcc, exec, s[10:11]
	s_cbranch_vccz .LBB0_1400
	s_barrier

;     DI bool next(int i, Unit& u) const { const long L = (long)i * G + c; if (L >= T.nwg) return false; T.map((int)L, u.pm, u.pn); u.seg = 0; return true; }
;     DI bool next(int i, Unit& u) const { const int ti = i / 3; const long L = (long)ti * G + c; if (L >= T.nwg) return false; T.map((int)L, u.pm, u.pn); u.seg = i - 3 * ti; return true; }
;     DI const char* aptr(const Unit& u) const { return A + (size_t)u.pm * ta + (size_t)kofs(u.seg) * 2; }
;     DI const char* bptr(const Unit& u) const { return B + (size_t)u.pn * tb + (size_t)kofs(u.seg) * 2; }
; #define PG8_STAGE(bufoff, gbase, voff) do { _Pragma("unroll") for (int _i = 0; _i < 2; ++_i) \
;         __builtin_amdgcn_global_load_lds((const unsigned*)((const char*)(gbase) + (voff)[_i]), (LAS unsigned*)(lds + (bufoff) + ldsw + _i * 8192), 16, 0, 0); } while (0)
; #define PG8_LDA(dst, b, h) do { _Pragma("unroll") for (int m = 0; m < 4; ++m) _Pragma("unroll") for (int k = 0; k < 2; ++k) dst[m][k] = *(const LAS bf16x8*)(lds + PG8_SA(b, h) + aoff + m * 2048 + k * 1024); } while (0)
; #define PG8_LDB(dst, b, h) do { _Pragma("unroll") for (int n = 0; n < 2; ++n) _Pragma("unroll") for (int k = 0; k < 2; ++k) dst[n][k] = *(const LAS bf16x8*)(lds + PG8_SB(b, h) + boff + n * 2048 + k * 1024); } while (0)
; #define PG8_BAR __builtin_amdgcn_s_barrier()
; template <class Epi, class Sched>
; DI void gemm_phase(LAS unsigned char* lds, const int wv, const int lda, const int ldb, const Sched& S, const Epi& E) {
;     ...
;         const bool has_next = S.next(ui + 1, nxt);
;         const char* nA = has_next ? S.aptr(nxt) : cA; const char* nB = has_next ? S.bptr(nxt) : cB;
;         for (int t = 0; t < nt; t += 2) {
;             const bool last = (t == nt - 2);
;             const char* a1 = cA + (size_t)(t + 1) * kstep;
;             const char* a2 = last ? nA : cA + (size_t)(t + 2) * kstep; const char* b2 = last ? nB : cB + (size_t)(t + 2) * kstep;
;             const char* a3 = a2 + kstep; const char* b3 = b2 + kstep;
;             PG8_LDB(B0, 0, 0); PG8_LDB(B1, 0, 1); PG8_SCHED; PG8_LDA(At, 0, 0); PG8_STAGE(PG8_SA(1, 1), a1 + hstepA, voffA);
;             PG8_WAIT_V(8); PG8_WAIT_L(0); PG8_BAR; PG8_MMA(0, 0, At, B0); PG8_MMA(0, 1, At, B1); PG8_BAR; PG8_SCHED;
;             PG8_LDA(At, 0, 1); PG8_STAGE(PG8_SB(0, 0), b2, voffB); PG8_STAGE(PG8_SB(0, 1), b2 + hstepB, voffB); PG8_STAGE(PG8_SA(0, 0), a2, voffA);
.LBB0_1477:
	s_add_i32 s56, 0, 0x10000
	s_add_i32 s58, 0, 0x14000
	v_add_u32_e32 v150, s56, v155
	v_add_u32_e32 v172, s58, v155
	ds_read_b128 v[128:131], v150
	ds_read_b128 v[142:145], v150 offset:1024
	ds_read_b128 v[146:149], v150 offset:2048
	ds_read_b128 v[150:153], v150 offset:3072
	ds_read_b128 v[160:163], v172
	ds_read_b128 v[164:167], v172 offset:1024
	ds_read_b128 v[168:171], v172 offset:2048
	ds_read_b128 v[172:175], v172 offset:3072
	v_lshl_add_u64 v[216:217], s[34:35], 0, v[138:139]
	s_add_i32 m0, s31, 0xc000
	ds_read_b128 v[176:179], v159
	ds_read_b128 v[180:183], v159 offset:1024
	ds_read_b128 v[188:191], v159 offset:2048
	ds_read_b128 v[196:199], v159 offset:3072
	ds_read_b128 v[200:203], v159 offset:4096
	ds_read_b128 v[204:207], v159 offset:5120
	ds_read_b128 v[208:211], v159 offset:6144
	ds_read_b128 v[212:215], v159 offset:7168
	global_load_lds_dwordx4 v[216:217], off
	v_lshl_add_u64 v[216:217], s[34:35], 0, v[140:141]
	s_add_i32 m0, s31, 0xe000
	s_nop 0
	global_load_lds_dwordx4 v[216:217], off
	s_add_u32 s36, s34, 0xffe00080
	s_addc_u32 s37, s35, -1
	s_cmpk_eq_i32 s55, 0x7c
	s_cselect_b32 s39, s0, s37
	s_cselect_b32 s38, s1, s36
	s_cselect_b32 s37, s11, s54
	s_cselect_b32 s36, s19, s23
	s_waitcnt vmcnt(8)
	s_waitcnt lgkmcnt(0)
	s_barrier
	s_waitcnt lgkmcnt(0)
	v_mfma_f32_16x16x32_bf16 v[124:127], v[128:131], v[176:179], v[124:127]
	v_mfma_f32_16x16x32_bf16 v[120:123], v[146:149], v[176:179], v[120:123]
	v_mfma_f32_16x16x32_bf16 v[108:111], v[128:131], v[188:191], v[108:111]
	v_mfma_f32_16x16x32_bf16 v[104:107], v[146:149], v[188:191], v[104:107]
	v_mfma_f32_16x16x32_bf16 v[96:99], v[128:131], v[200:203], v[96:99]
	v_mfma_f32_16x16x32_bf16 v[88:91], v[146:149], v[200:203], v[88:91]
	v_mfma_f32_16x16x32_bf16 v[80:83], v[128:131], v[208:211], v[80:83]
	v_mfma_f32_16x16x32_bf16 v[72:75], v[146:149], v[208:211], v[72:75]
	v_mfma_f32_16x16x32_bf16 v[124:127], v[142:145], v[180:183], v[124:127]
	v_mfma_f32_16x16x32_bf16 v[120:123], v[150:153], v[180:183], v[120:123]
	v_mfma_f32_16x16x32_bf16 v[108:111], v[142:145], v[196:199], v[108:111]
	v_mfma_f32_16x16x32_bf16 v[104:107], v[150:153], v[196:199], v[104:107]
	v_mfma_f32_16x16x32_bf16 v[96:99], v[142:145], v[204:207], v[96:99]
	v_mfma_f32_16x16x32_bf16 v[88:91], v[150:153], v[204:207], v[88:91]
	v_mfma_f32_16x16x32_bf16 v[80:83], v[142:145], v[212:215], v[80:83]
	v_mfma_f32_16x16x32_bf16 v[72:75], v[150:153], v[212:215], v[72:75]
	v_mfma_f32_16x16x32_bf16 v[116:119], v[160:163], v[176:179], v[116:119]
	v_mfma_f32_16x16x32_bf16 v[112:115], v[168:171], v[176:179], v[112:115]
	v_mfma_f32_16x16x32_bf16 v[100:103], v[160:163], v[188:191], v[100:103]
	v_mfma_f32_16x16x32_bf16 v[92:95], v[168:171], v[188:191], v[92:95]
	v_mfma_f32_16x16x32_bf16 v[84:87], v[160:163], v[200:203], v[84:87]
	v_mfma_f32_16x16x32_bf16 v[76:79], v[168:171], v[200:203], v[76:79]
	v_mfma_f32_16x16x32_bf16 v[68:71], v[160:163], v[208:211], v[68:71]
	v_mfma_f32_16x16x32_bf16 v[64:67], v[168:171], v[208:211], v[64:67]
	v_mfma_f32_16x16x32_bf16 v[116:119], v[164:167], v[180:183], v[116:119]
	v_mfma_f32_16x16x32_bf16 v[112:115], v[172:175], v[180:183], v[112:115]
	v_mfma_f32_16x16x32_bf16 v[100:103], v[164:167], v[196:199], v[100:103]
	v_mfma_f32_16x16x32_bf16 v[92:95], v[172:175], v[196:199], v[92:95]
	v_mfma_f32_16x16x32_bf16 v[84:87], v[164:167], v[204:207], v[84:87]
	v_mfma_f32_16x16x32_bf16 v[76:79], v[172:175], v[204:207], v[76:79]
	v_mfma_f32_16x16x32_bf16 v[68:71], v[164:167], v[212:215], v[68:71]
	v_mfma_f32_16x16x32_bf16 v[64:67], v[172:175], v[212:215], v[64:67]
	s_barrier
	s_add_i32 s56, s56, s43
	v_lshl_add_u64 v[216:217], s[36:37], 0, v[184:185]
	s_mov_b32 m0, s56
	ds_read_b128 v[176:179], v159 offset:16384
	ds_read_b128 v[180:183], v159 offset:17408
	ds_read_b128 v[188:191], v159 offset:18432
	ds_read_b128 v[196:199], v159 offset:19456
	ds_read_b128 v[200:203], v159 offset:20480
	ds_read_b128 v[204:207], v159 offset:21504
	ds_read_b128 v[208:211], v159 offset:22528
	ds_read_b128 v[212:215], v159 offset:23552
	global_load_lds_dwordx4 v[216:217], off
	s_add_i32 m0, s56, 0x2000
	s_add_u32 s56, s36, 0x200000
	v_lshl_add_u64 v[218:219], s[36:37], 0, v[136:137]
	s_addc_u32 s57, s37, 0
	s_add_i32 s58, s58, s43
	global_load_lds_dwordx4 v[218:219], off
	v_lshl_add_u64 v[220:221], s[56:57], 0, v[184:185]
	s_mov_b32 m0, s58
	v_lshl_add_u64 v[222:223], s[38:39], 0, v[134:135]
	global_load_lds_dwordx4 v[220:221], off
	v_lshl_add_u64 v[220:221], s[56:57], 0, v[136:137]
	s_add_i32 m0, s58, 0x2000
	s_nop 0
	global_load_lds_dwordx4 v[220:221], off
	v_lshl_add_u64 v[220:221], s[38:39], 0, v[132:133]
	s_mov_b32 m0, s31
	s_nop 0
	global_load_lds_dwordx4 v[220:221], off
	s_mov_b32 m0, s44
	s_nop 0
	global_load_lds_dwordx4 v[222:223], off
	s_waitcnt vmcnt(8)
	s_waitcnt lgkmcnt(0)
	s_barrier
; #define PG8_STAGE(bufoff, gbase, voff) do { _Pragma("unroll") for (int _i = 0; _i < 2; ++_i) \
;         __builtin_amdgcn_global_load_lds((const unsigned*)((const char*)(gbase) + (voff)[_i]), (LAS unsigned*)(lds + (bufoff) + ldsw + _i * 8192), 16, 0, 0); } while (0)
; #define PG8_LDA(dst, b, h) do { _Pragma("unroll") for (int m = 0; m < 4; ++m) _Pragma("unroll") for (int k = 0; k < 2; ++k) dst[m][k] = *(const LAS bf16x8*)(lds + PG8_SA(b, h) + aoff + m * 2048 + k * 1024); } while (0)
; #define PG8_LDB(dst, b, h) do { _Pragma("unroll") for (int n = 0; n < 2; ++n) _Pragma("unroll") for (int k = 0; k < 2; ++k) dst[n][k] = *(const LAS bf16x8*)(lds + PG8_SB(b, h) + boff + n * 2048 + k * 1024); } while (0)
; #define PG8_MMA(ai, bj, At, Bt) do { __builtin_amdgcn_s_setprio(1); _Pragma("unroll") for (int m = 0; m < 4; ++m) _Pragma("unroll") for (int n = 0; n < 2; ++n) _Pragma("unroll") for (int k = 0; k < 2; ++k) \
;         acc[ai][bj][m][n] = __builtin_amdgcn_mfma_f32_16x16x32_bf16(Bt[n][k], At[m][k], acc[ai][bj][m][n], 0, 0, 0); __builtin_amdgcn_s_setprio(0); } while (0)
; #define PG8_WAIT_V(n) asm volatile("s_waitcnt vmcnt(" #n ")" ::: "memory")
; #define PG8_WAIT_L(n) asm volatile("s_waitcnt lgkmcnt(" #n ")" ::: "memory")
; #define PG8_BAR __builtin_amdgcn_s_barrier()
; #define PG8_SCHED __builtin_amdgcn_sched_barrier(0)
; template <class Epi, class Sched>
; DI void gemm_phase(LAS unsigned char* lds, const int wv, const int lda, const int ldb, const Sched& S, const Epi& E) {
;     ...
;             PG8_WAIT_V(8); PG8_WAIT_L(0); PG8_BAR; PG8_MMA(1, 0, At, B0); PG8_MMA(1, 1, At, B1); PG8_BAR; PG8_SCHED;
;             PG8_LDB(B0, 1, 0); PG8_LDB(B1, 1, 1); PG8_SCHED; PG8_LDA(At, 1, 0); PG8_STAGE(PG8_SA(0, 1), a2 + hstepA, voffA);
;             PG8_WAIT_V(8); PG8_WAIT_L(0); PG8_BAR; PG8_MMA(0, 0, At, B0); PG8_MMA(0, 1, At, B1); PG8_BAR; PG8_SCHED;
	s_waitcnt lgkmcnt(0)
	v_mfma_f32_16x16x32_bf16 v[60:63], v[128:131], v[176:179], v[60:63]
	v_mfma_f32_16x16x32_bf16 v[56:59], v[146:149], v[176:179], v[56:59]
	v_mfma_f32_16x16x32_bf16 v[48:51], v[128:131], v[188:191], v[48:51]
	v_mfma_f32_16x16x32_bf16 v[40:43], v[146:149], v[188:191], v[40:43]
	v_mfma_f32_16x16x32_bf16 v[32:35], v[128:131], v[200:203], v[32:35]
	v_mfma_f32_16x16x32_bf16 v[24:27], v[146:149], v[200:203], v[24:27]
	v_mfma_f32_16x16x32_bf16 v[16:19], v[128:131], v[208:211], v[16:19]
	v_mfma_f32_16x16x32_bf16 v[8:11], v[146:149], v[208:211], v[8:11]
	v_mfma_f32_16x16x32_bf16 v[60:63], v[142:145], v[180:183], v[60:63]
	v_mfma_f32_16x16x32_bf16 v[56:59], v[150:153], v[180:183], v[56:59]
	v_mfma_f32_16x16x32_bf16 v[48:51], v[142:145], v[196:199], v[48:51]
	v_mfma_f32_16x16x32_bf16 v[40:43], v[150:153], v[196:199], v[40:43]
	v_mfma_f32_16x16x32_bf16 v[32:35], v[142:145], v[204:207], v[32:35]
	v_mfma_f32_16x16x32_bf16 v[24:27], v[150:153], v[204:207], v[24:27]
	v_mfma_f32_16x16x32_bf16 v[16:19], v[142:145], v[212:215], v[16:19]
	v_mfma_f32_16x16x32_bf16 v[8:11], v[150:153], v[212:215], v[8:11]
	v_mfma_f32_16x16x32_bf16 v[52:55], v[160:163], v[176:179], v[52:55]
	v_mfma_f32_16x16x32_bf16 v[44:47], v[168:171], v[176:179], v[44:47]
	v_mfma_f32_16x16x32_bf16 v[36:39], v[160:163], v[188:191], v[36:39]
	v_mfma_f32_16x16x32_bf16 v[28:31], v[168:171], v[188:191], v[28:31]
	v_mfma_f32_16x16x32_bf16 v[20:23], v[160:163], v[200:203], v[20:23]
	v_mfma_f32_16x16x32_bf16 v[12:15], v[168:171], v[200:203], v[12:15]
	v_mfma_f32_16x16x32_bf16 v[4:7], v[160:163], v[208:211], v[4:7]
	v_mfma_f32_16x16x32_bf16 v[0:3], v[168:171], v[208:211], v[0:3]
	v_mfma_f32_16x16x32_bf16 v[52:55], v[164:167], v[180:183], v[52:55]
	v_mfma_f32_16x16x32_bf16 v[44:47], v[172:175], v[180:183], v[44:47]
	v_mfma_f32_16x16x32_bf16 v[36:39], v[164:167], v[196:199], v[36:39]
	v_mfma_f32_16x16x32_bf16 v[28:31], v[172:175], v[196:199], v[28:31]
	v_mfma_f32_16x16x32_bf16 v[20:23], v[164:167], v[204:207], v[20:23]
	v_mfma_f32_16x16x32_bf16 v[12:15], v[172:175], v[204:207], v[12:15]
	v_mfma_f32_16x16x32_bf16 v[4:7], v[164:167], v[212:215], v[4:7]
	v_mfma_f32_16x16x32_bf16 v[0:3], v[172:175], v[212:215], v[0:3]
	s_barrier
	s_add_i32 s56, 0, 0x18000
	s_add_i32 s57, 0, 0x1c000
	v_add_u32_e32 v150, s56, v155
	v_add_u32_e32 v172, s57, v155
	ds_read_b128 v[128:131], v150
	ds_read_b128 v[142:145], v150 offset:1024
	ds_read_b128 v[146:149], v150 offset:2048
	ds_read_b128 v[150:153], v150 offset:3072
	ds_read_b128 v[160:163], v172
	ds_read_b128 v[164:167], v172 offset:1024
	ds_read_b128 v[168:171], v172 offset:2048
	ds_read_b128 v[172:175], v172 offset:3072
	s_add_u32 s38, s38, 0x200000
	s_addc_u32 s39, s39, 0
	s_mov_b32 m0, s45
	v_lshl_add_u64 v[234:235], s[38:39], 0, v[132:133]
	ds_read_b128 v[176:179], v159 offset:32768
	ds_read_b128 v[180:183], v159 offset:33792
	ds_read_b128 v[188:191], v159 offset:34816
	ds_read_b128 v[196:199], v159 offset:35840
	ds_read_b128 v[200:203], v159 offset:36864
	ds_read_b128 v[204:207], v159 offset:37888
	ds_read_b128 v[208:211], v159 offset:38912
	ds_read_b128 v[212:215], v159 offset:39936
	global_load_lds_dwordx4 v[234:235], off
	v_lshl_add_u64 v[234:235], s[38:39], 0, v[134:135]
	s_mov_b32 m0, s46
	s_nop 0
	global_load_lds_dwordx4 v[234:235], off
	s_waitcnt vmcnt(8)
	s_waitcnt lgkmcnt(0)
	s_barrier
	s_waitcnt lgkmcnt(0)
	v_mfma_f32_16x16x32_bf16 v[124:127], v[128:131], v[176:179], v[124:127]
	v_mfma_f32_16x16x32_bf16 v[120:123], v[146:149], v[176:179], v[120:123]
	v_mfma_f32_16x16x32_bf16 v[108:111], v[128:131], v[188:191], v[108:111]
	v_mfma_f32_16x16x32_bf16 v[104:107], v[146:149], v[188:191], v[104:107]
	v_mfma_f32_16x16x32_bf16 v[96:99], v[128:131], v[200:203], v[96:99]
	v_mfma_f32_16x16x32_bf16 v[88:91], v[146:149], v[200:203], v[88:91]
	v_mfma_f32_16x16x32_bf16 v[80:83], v[128:131], v[208:211], v[80:83]
	v_mfma_f32_16x16x32_bf16 v[72:75], v[146:149], v[208:211], v[72:75]
	v_mfma_f32_16x16x32_bf16 v[124:127], v[142:145], v[180:183], v[124:127]
	v_mfma_f32_16x16x32_bf16 v[120:123], v[150:153], v[180:183], v[120:123]
	v_mfma_f32_16x16x32_bf16 v[108:111], v[142:145], v[196:199], v[108:111]
	v_mfma_f32_16x16x32_bf16 v[104:107], v[150:153], v[196:199], v[104:107]
	v_mfma_f32_16x16x32_bf16 v[96:99], v[142:145], v[204:207], v[96:99]
	v_mfma_f32_16x16x32_bf16 v[88:91], v[150:153], v[204:207], v[88:91]
	v_mfma_f32_16x16x32_bf16 v[80:83], v[142:145], v[212:215], v[80:83]
	v_mfma_f32_16x16x32_bf16 v[72:75], v[150:153], v[212:215], v[72:75]
	v_mfma_f32_16x16x32_bf16 v[116:119], v[160:163], v[176:179], v[116:119]
	v_mfma_f32_16x16x32_bf16 v[112:115], v[168:171], v[176:179], v[112:115]
	v_mfma_f32_16x16x32_bf16 v[100:103], v[160:163], v[188:191], v[100:103]
	v_mfma_f32_16x16x32_bf16 v[92:95], v[168:171], v[188:191], v[92:95]
	v_mfma_f32_16x16x32_bf16 v[84:87], v[160:163], v[200:203], v[84:87]
	v_mfma_f32_16x16x32_bf16 v[76:79], v[168:171], v[200:203], v[76:79]
	v_mfma_f32_16x16x32_bf16 v[68:71], v[160:163], v[208:211], v[68:71]
	v_mfma_f32_16x16x32_bf16 v[64:67], v[168:171], v[208:211], v[64:67]
	v_mfma_f32_16x16x32_bf16 v[116:119], v[164:167], v[180:183], v[116:119]
	v_mfma_f32_16x16x32_bf16 v[112:115], v[172:175], v[180:183], v[112:115]
	v_mfma_f32_16x16x32_bf16 v[100:103], v[164:167], v[196:199], v[100:103]
	v_mfma_f32_16x16x32_bf16 v[92:95], v[172:175], v[196:199], v[92:95]
	v_mfma_f32_16x16x32_bf16 v[84:87], v[164:167], v[204:207], v[84:87]
	v_mfma_f32_16x16x32_bf16 v[76:79], v[172:175], v[204:207], v[76:79]
	v_mfma_f32_16x16x32_bf16 v[68:71], v[164:167], v[212:215], v[68:71]
	v_mfma_f32_16x16x32_bf16 v[64:67], v[172:175], v[212:215], v[64:67]
	s_barrier
; #define PG8_STAGE(bufoff, gbase, voff) do { _Pragma("unroll") for (int _i = 0; _i < 2; ++_i) \
;         __builtin_amdgcn_global_load_lds((const unsigned*)((const char*)(gbase) + (voff)[_i]), (LAS unsigned*)(lds + (bufoff) + ldsw + _i * 8192), 16, 0, 0); } while (0)
; #define PG8_LDA(dst, b, h) do { _Pragma("unroll") for (int m = 0; m < 4; ++m) _Pragma("unroll") for (int k = 0; k < 2; ++k) dst[m][k] = *(const LAS bf16x8*)(lds + PG8_SA(b, h) + aoff + m * 2048 + k * 1024); } while (0)
; #define PG8_MMA(ai, bj, At, Bt) do { __builtin_amdgcn_s_setprio(1); _Pragma("unroll") for (int m = 0; m < 4; ++m) _Pragma("unroll") for (int n = 0; n < 2; ++n) _Pragma("unroll") for (int k = 0; k < 2; ++k) \
;         acc[ai][bj][m][n] = __builtin_amdgcn_mfma_f32_16x16x32_bf16(Bt[n][k], At[m][k], acc[ai][bj][m][n], 0, 0, 0); __builtin_amdgcn_s_setprio(0); } while (0)
; #define PG8_WAIT_V(n) asm volatile("s_waitcnt vmcnt(" #n ")" ::: "memory")
; #define PG8_WAIT_L(n) asm volatile("s_waitcnt lgkmcnt(" #n ")" ::: "memory")
; #define PG8_BAR __builtin_amdgcn_s_barrier()
; #define PG8_SCHED __builtin_amdgcn_sched_barrier(0)
; template <class Epi, class Sched>
; DI void gemm_phase(LAS unsigned char* lds, const int wv, const int lda, const int ldb, const Sched& S, const Epi& E) {
;     ...
;             PG8_LDA(At, 1, 1); PG8_STAGE(PG8_SB(1, 0), b3, voffB); PG8_STAGE(PG8_SB(1, 1), b3 + hstepB, voffB); PG8_STAGE(PG8_SA(1, 0), a3, voffA);
;             PG8_WAIT_V(8); PG8_WAIT_L(0); PG8_BAR; PG8_MMA(1, 0, At, B0); PG8_MMA(1, 1, At, B1); PG8_BAR; PG8_SCHED;
;         }
;         if (wr == 0) PG8_BAR;
	s_add_i32 s38, s56, s43
	v_lshl_add_u64 v[216:217], v[216:217], 0, s[28:29]
	s_mov_b32 m0, s38
	ds_read_b128 v[176:179], v159 offset:49152
	ds_read_b128 v[180:183], v159 offset:50176
	ds_read_b128 v[188:191], v159 offset:51200
	ds_read_b128 v[196:199], v159 offset:52224
	ds_read_b128 v[200:203], v159 offset:53248
	ds_read_b128 v[204:207], v159 offset:54272
	ds_read_b128 v[208:211], v159 offset:55296
	ds_read_b128 v[212:215], v159 offset:56320
	global_load_lds_dwordx4 v[216:217], off
	s_add_i32 m0, s38, 0x2000
	s_add_u32 s36, s36, 0x200080
	v_lshl_add_u64 v[216:217], v[218:219], 0, s[28:29]
	s_addc_u32 s37, s37, 0
	s_add_i32 s38, s57, s43
	global_load_lds_dwordx4 v[216:217], off
	v_lshl_add_u64 v[216:217], s[36:37], 0, v[184:185]
	s_mov_b32 m0, s38
	s_nop 0
	global_load_lds_dwordx4 v[216:217], off
	v_lshl_add_u64 v[216:217], s[36:37], 0, v[136:137]
	s_add_i32 m0, s38, 0x2000
	s_nop 0
	global_load_lds_dwordx4 v[216:217], off
	v_lshl_add_u64 v[216:217], v[220:221], 0, s[28:29]
	s_mov_b32 m0, s47
	s_nop 0
	global_load_lds_dwordx4 v[216:217], off
	v_lshl_add_u64 v[216:217], v[222:223], 0, s[28:29]
	s_mov_b32 m0, s48
	s_nop 0
	global_load_lds_dwordx4 v[216:217], off
	s_waitcnt vmcnt(8)
	s_waitcnt lgkmcnt(0)
	s_barrier
	s_waitcnt lgkmcnt(0)
	v_mfma_f32_16x16x32_bf16 v[60:63], v[128:131], v[176:179], v[60:63]
	v_mfma_f32_16x16x32_bf16 v[56:59], v[146:149], v[176:179], v[56:59]
	v_mfma_f32_16x16x32_bf16 v[48:51], v[128:131], v[188:191], v[48:51]
	v_mfma_f32_16x16x32_bf16 v[40:43], v[146:149], v[188:191], v[40:43]
	v_mfma_f32_16x16x32_bf16 v[32:35], v[128:131], v[200:203], v[32:35]
	v_mfma_f32_16x16x32_bf16 v[24:27], v[146:149], v[200:203], v[24:27]
	v_mfma_f32_16x16x32_bf16 v[16:19], v[128:131], v[208:211], v[16:19]
	v_mfma_f32_16x16x32_bf16 v[8:11], v[146:149], v[208:211], v[8:11]
	v_mfma_f32_16x16x32_bf16 v[60:63], v[142:145], v[180:183], v[60:63]
	v_mfma_f32_16x16x32_bf16 v[56:59], v[150:153], v[180:183], v[56:59]
	v_mfma_f32_16x16x32_bf16 v[48:51], v[142:145], v[196:199], v[48:51]
	v_mfma_f32_16x16x32_bf16 v[40:43], v[150:153], v[196:199], v[40:43]
	v_mfma_f32_16x16x32_bf16 v[32:35], v[142:145], v[204:207], v[32:35]
	v_mfma_f32_16x16x32_bf16 v[24:27], v[150:153], v[204:207], v[24:27]
	v_mfma_f32_16x16x32_bf16 v[16:19], v[142:145], v[212:215], v[16:19]
	v_mfma_f32_16x16x32_bf16 v[8:11], v[150:153], v[212:215], v[8:11]
	v_mfma_f32_16x16x32_bf16 v[52:55], v[160:163], v[176:179], v[52:55]
	v_mfma_f32_16x16x32_bf16 v[44:47], v[168:171], v[176:179], v[44:47]
	v_mfma_f32_16x16x32_bf16 v[36:39], v[160:163], v[188:191], v[36:39]
	v_mfma_f32_16x16x32_bf16 v[28:31], v[168:171], v[188:191], v[28:31]
	v_mfma_f32_16x16x32_bf16 v[20:23], v[160:163], v[200:203], v[20:23]
	v_mfma_f32_16x16x32_bf16 v[12:15], v[168:171], v[200:203], v[12:15]
	v_mfma_f32_16x16x32_bf16 v[4:7], v[160:163], v[208:211], v[4:7]
	v_mfma_f32_16x16x32_bf16 v[0:3], v[168:171], v[208:211], v[0:3]
	v_mfma_f32_16x16x32_bf16 v[52:55], v[164:167], v[180:183], v[52:55]
	v_mfma_f32_16x16x32_bf16 v[44:47], v[172:175], v[180:183], v[44:47]
	v_mfma_f32_16x16x32_bf16 v[36:39], v[164:167], v[196:199], v[36:39]
	v_mfma_f32_16x16x32_bf16 v[28:31], v[172:175], v[196:199], v[28:31]
	v_mfma_f32_16x16x32_bf16 v[20:23], v[164:167], v[204:207], v[20:23]
	v_mfma_f32_16x16x32_bf16 v[12:15], v[172:175], v[204:207], v[12:15]
	v_mfma_f32_16x16x32_bf16 v[4:7], v[164:167], v[212:215], v[4:7]
	v_mfma_f32_16x16x32_bf16 v[0:3], v[172:175], v[212:215], v[0:3]
	s_barrier
	s_add_i32 s55, s55, 2
	s_add_u32 s34, s34, 0x100
	s_addc_u32 s35, s35, 0
	s_add_u32 s23, s23, 0x100
	s_addc_u32 s54, s54, 0
	s_cmpk_gt_u32 s55, 0x7d
	s_cbranch_scc0 .LBB0_1477
	s_and_b64 vcc, exec, s[14:15]
	s_cbranch_vccz .LBB0_1480
	s_barrier
